# attention: removed 8 permlane32_swap per softmax finish by permuting V tile rows in the LDS-DMA source address (key order inside 16-key groups)
# baseline (speedup 1.0000x reference)
; #define LAS __attribute__((address_space(3)))
; __device__ __forceinline__ const float* inp(int k) { const CAS cfptr* p = (const CAS cfptr*)__builtin_amdgcn_kernarg_segment_ptr(); asm volatile("" : "+s"(p)); return p[k]; }
; __device__ __forceinline__ int tid_() { int t = threadIdx.x; asm volatile("" : "+v"(t)); return t; }
; __device__ __forceinline__ int v_rd_base(int lane) { return ((lane & 3) << 3) | (((lane >> 2) & 3) << 6) | (((lane >> 4) & 1) << 5) | (((lane >> 5) & 1) << 8); }
; template <bool SHIFT> __device__ __forceinline__ void attn_dense_body(const bf16* __restrict__ Qb, const bf16* __restrict__ Kh, const bf16* __restrict__ Vh, bf16* __restrict__ Ob, int seq, char* lds, LAS unsigned char* ldsl, float negB, const float* __restrict__ gq, int qpos0) {
;     ...
;   const int vb0 = (int)(uintptr_t)V_lds + v_rd_base(lane);
;   const int widu = __builtin_amdgcn_readfirstlane(wid);
;   const int kr0 = 8 * wid + (lane >> 4), kr1 = kr0 + 4, kp = lane & 15;
;   const int vkk = 8 * wid + ((lane & 31) >> 2), vk = (vkk & ~0xC) | ((vkk & 4) << 1) | ((vkk & 8) >> 1), vcc = 32 * (lane >> 5) + 8 * (lane & 3);
;   const bf16* kg0 = Kh + (long)kr0 * LDK + ((kp ^ (kr0 & 7)) * 8); const bf16* kg1 = Kh + (long)kr1 * LDK + ((kp ^ (kr1 & 7)) * 8); const bf16* vg = Vh + (long)vk * LDV + vcc;
;   LAS unsigned char* const lV = ldsl; LAS unsigned char* const lK = ldsl + 3 * SHM_V;
; __global__ void __launch_bounds__(NWAVES * 64, 2) mk_fwd(Args args) {
;     ...
;         { const float* gq = inp(26); const float* gk = inp(27); const int l = tid_() & 63; float a = fabsf(gq[l]), c = fabsf(gk[l]);
;           if (l < 32) { a = fmaxf(a, fabsf(gq[64 + l])); c = fmaxf(c, fabsf(gk[64 + l])); }
; #pragma unroll
;           for (int o = 1; o < 64; o <<= 1) { a = fmaxf(a, __shfl_xor(a, o)); c = fmaxf(c, __shfl_xor(c, o)); }
;           negB = -(96.0f * 0.10206207261596575f * 1.4426950408889634f * 1.01f) * a * c;
;           negB = __uint_as_float(__builtin_amdgcn_readfirstlane(__float_as_uint(negB))); }
.LBB0_1587:
	s_or_b64 exec, exec, s[8:9]
	v_mbcnt_lo_u32_b32 v0, -1, 0
	v_mbcnt_hi_u32_b32 v0, -1, v0
	v_and_b32_e32 v3, 64, v0
	v_add_u32_e32 v3, 64, v3
	v_xor_b32_e32 v4, 1, v0
	v_cmp_lt_i32_e32 vcc, v4, v3
	s_ashr_i32 s9, s2, 31
	s_lshr_b32 s9, s9, 29
	v_cndmask_b32_e32 v4, v0, v4, vcc
	v_lshlrev_b32_e32 v4, 2, v4
	ds_bpermute_b32 v5, v4, v2
	v_max_f32_e32 v2, v2, v2
	ds_bpermute_b32 v4, v4, v1
	v_max_f32_e32 v1, v1, v1
	s_add_i32 s9, s2, s9
	s_waitcnt lgkmcnt(1)
	v_max_f32_e32 v5, v5, v5
	v_max_f32_e32 v2, v2, v5
	v_xor_b32_e32 v5, 2, v0
	v_cmp_lt_i32_e32 vcc, v5, v3
	s_waitcnt lgkmcnt(0)
	v_max_f32_e32 v4, v4, v4
	v_max_f32_e32 v1, v1, v4
	v_cndmask_b32_e32 v5, v0, v5, vcc
	v_lshlrev_b32_e32 v5, 2, v5
	ds_bpermute_b32 v6, v5, v2
	ds_bpermute_b32 v4, v5, v1
	s_and_b32 s10, s9, -8
	s_ashr_i32 s8, s82, 3
	s_sub_i32 s10, s2, s10
	s_waitcnt lgkmcnt(1)
	v_max_f32_e32 v5, v6, v6
	v_max_f32_e32 v2, v2, v5
	v_xor_b32_e32 v5, 4, v0
	v_cmp_lt_i32_e32 vcc, v5, v3
	s_waitcnt lgkmcnt(0)
	v_max_f32_e32 v4, v4, v4
	v_max_f32_e32 v1, v1, v4
	v_cndmask_b32_e32 v5, v0, v5, vcc
	v_lshlrev_b32_e32 v5, 2, v5
	ds_bpermute_b32 v6, v5, v2
	ds_bpermute_b32 v4, v5, v1
	s_mul_i32 s8, s8, s10
	s_ashr_i32 s9, s9, 3
	s_and_b32 s3, s82, 7
	s_waitcnt lgkmcnt(1)
	v_max_f32_e32 v5, v6, v6
	v_max_f32_e32 v2, v2, v5
	v_xor_b32_e32 v5, 8, v0
	v_cmp_lt_i32_e32 vcc, v5, v3
	s_waitcnt lgkmcnt(0)
	v_max_f32_e32 v4, v4, v4
	v_max_f32_e32 v1, v1, v4
	v_cndmask_b32_e32 v5, v0, v5, vcc
	v_lshlrev_b32_e32 v5, 2, v5
	ds_bpermute_b32 v6, v5, v2
	ds_bpermute_b32 v4, v5, v1
	s_add_i32 s8, s8, s9
	s_cmp_eq_u32 s3, 0
	s_cselect_b32 s3, s8, s2
	s_waitcnt lgkmcnt(1)
	v_max_f32_e32 v5, v6, v6
	v_max_f32_e32 v2, v2, v5
	v_xor_b32_e32 v5, 16, v0
	v_cmp_lt_i32_e32 vcc, v5, v3
	s_waitcnt lgkmcnt(0)
	v_max_f32_e32 v4, v4, v4
	v_max_f32_e32 v1, v1, v4
	v_cndmask_b32_e32 v5, v0, v5, vcc
	v_lshlrev_b32_e32 v5, 2, v5
	ds_bpermute_b32 v6, v5, v2
	ds_bpermute_b32 v4, v5, v1
	s_cmpk_gt_i32 s3, 0x7ff
	s_waitcnt lgkmcnt(1)
	v_max_f32_e32 v5, v6, v6
	v_max_f32_e32 v2, v2, v5
	v_xor_b32_e32 v5, 32, v0
	v_cmp_lt_i32_e32 vcc, v5, v3
	s_waitcnt lgkmcnt(0)
	v_max_f32_e32 v4, v4, v4
	v_max_f32_e32 v1, v1, v4
	v_cndmask_b32_e32 v0, v0, v5, vcc
	v_lshlrev_b32_e32 v0, 2, v0
	ds_bpermute_b32 v3, v0, v2
	ds_bpermute_b32 v0, v0, v1
	s_waitcnt lgkmcnt(1)
	v_max_f32_e32 v3, v3, v3
	v_max_f32_e32 v2, v2, v3
	s_waitcnt lgkmcnt(0)
	v_max_f32_e32 v0, v0, v0
	v_max_f32_e32 v0, v1, v0
	v_mul_f32_e32 v1, 0xc1646ddd, v2
	v_mul_f32_e32 v0, v0, v1
	s_nop 0
	v_readfirstlane_b32 s40, v0
	s_cbranch_scc1 .LBB0_1606
	s_load_dwordx2 s[10:11], s[4:5], 0xf0
	s_load_dwordx2 s[12:13], s[6:7], 0xe8
	v_and_b32_e32 v1, 63, v188
	v_and_b32_e32 v3, 0x3c0, v188
	s_add_i32 s4, 0, 0x18000
	v_cmp_gt_u32_e64 s[6:7], 32, v1
	v_lshl_add_u32 v113, v3, 2, s4
	v_lshlrev_b32_e32 v1, 3, v188
	v_lshlrev_b32_e32 v3, 4, v188
	v_lshlrev_b32_e32 v5, 1, v188
	v_lshrrev_b32_e32 v109, 6, v188
	v_and_b32_e32 v4, 0xc0, v3
	v_and_b32_e32 v5, 32, v5
	v_and_b32_e32 v6, 0x118, v1
	v_or3_b32 v4, v5, v4, v6
	v_lshlrev_b32_e32 v5, 3, v109
	v_bfe_u32 v6, v188, 4, 2
	v_bfe_u32 v9, v188, 2, 3
	s_movk_i32 s5, 0x73
	v_bfe_u32 v2, v188, 5, 1
	v_or_b32_e32 v7, v5, v6
	v_or_b32_e32 v5, v5, v9
	v_lshrrev_b32_e32 v9, 1, v188
	v_lshrrev_b32_e32 v10, 4, v188
	v_and_b32_e32 v108, 31, v188
	v_and_b32_e32 v9, 8, v9
	v_and_b32_e32 v10, 4, v10
	v_lshlrev_b32_e32 v117, 4, v2
	s_nop 0
	v_lshlrev_b32_e32 v10, 8, v108
	v_and_b32_e32 v3, 0x70, v3
	v_or_b32_e32 v11, 32, v117
	v_bitop3_b32 v147, v11, v10, v3 bitop3:0xde
	v_or_b32_e32 v11, 64, v117
	s_cmp_lg_u32 0, -1
	v_bitop3_b32 v148, v11, v10, v3 bitop3:0xde
	v_or_b32_e32 v11, 0x60, v117
	v_lshlrev_b32_e32 v110, 3, v2
	s_cselect_b32 s4, 0, 0
	v_bitop3_b32 v149, v11, v10, v3 bitop3:0xde
	v_or_b32_e32 v11, 0x80, v117
	v_lshlrev_b32_e32 v118, 13, v2
	v_or_b32_e32 v2, 0xc0, v117
	v_mov_b32_e32 v81, 0
	v_add_u32_e32 v115, s4, v4
	v_and_b32_e32 v9, 32, v188
	v_bitop3_b32 v150, v11, v10, v3 bitop3:0xde
	v_or_b32_e32 v11, 0xa0, v117
	s_addk_i32 s4, 0x4000
	v_bitop3_b32 v154, v2, v10, v3 bitop3:0xde
	v_mov_b32_e32 v2, 0xc2c80000
	v_lshlrev_b32_e32 v80, 8, v7
	v_and_or_b32 v1, v1, 24, v9
	v_bitop3_b32 v146, v117, v10, v3 bitop3:0xde
	v_bitop3_b32 v151, v11, v10, v3 bitop3:0xde
	v_add_u32_e32 v152, s4, v4
	v_cmp_nlt_f32_e64 s[8:9], s40, v2
	s_waitcnt lgkmcnt(0)
	v_lshl_add_u64 v[2:3], s[10:11], 0, v[80:81]
	s_mov_b64 s[4:5], 0x12c00000
	v_lshlrev_b32_e32 v80, 7, v5
	v_lshl_or_b32 v111, v109, 5, v108
	v_and_b32_e32 v8, 15, v188
	v_lshl_add_u64 v[120:121], v[2:3], 0, s[4:5]
	v_lshl_add_u64 v[2:3], s[10:11], 0, v[80:81]
	v_lshlrev_b32_e32 v4, 1, v1
	v_mov_b32_e32 v5, v81
	v_lshlrev_b32_e32 v1, 8, v6
	v_mul_u32_u24_e32 v0, 0x600, v111
	v_bitop3_b32 v9, v6, v188, 15 bitop3:0x78
	v_bitop3_b32 v8, v6, v8, 4 bitop3:0x36
	s_add_u32 s42, s10, 0xe800000
	v_lshl_add_u64 v[2:3], v[2:3], 0, v[4:5]
	s_mov_b64 s[4:5], 0x1bc00000
	v_lshl_or_b32 v1, v109, 11, v1
	v_lshlrev_b32_e32 v112, 3, v9
	v_lshlrev_b32_e32 v114, 3, v8
	s_movk_i32 s41, 0x4000
	v_lshl_add_u32 v153, v108, 2, v113
	v_lshlrev_b32_e32 v116, 15, v109
	v_mov_b32_e32 v119, v81
	s_addc_u32 s43, s11, 0
	v_lshl_add_u64 v[122:123], v[2:3], 0, s[4:5]
	v_lshl_or_b32 v124, v9, 4, v1
	v_mov_b32_e32 v125, v81
	v_lshl_or_b32 v126, v8, 4, v1
	v_mov_b32_e32 v127, v81
	v_or_b32_e32 v128, v80, v4
	v_mov_b32_e32 v129, v81
	v_lshlrev_b32_e32 v130, 1, v0
	v_lshlrev_b32_e32 v132, 1, v110
	v_mov_b32_e32 v155, 0x358637bd
	s_mov_b32 s44, 0x800000
	s_mov_b64 s[14:15], 0x400
	s_mov_b32 s45, 0xc000
	s_mov_b64 s[16:17], 0x4000
	s_mov_b64 s[18:19], 0x4400
	s_mov_b64 s[20:21], 0x2000
	s_mov_b64 s[22:23], 0x12c08000
	s_mov_b64 s[24:25], 0x12c08400
	s_mov_b64 s[26:27], 0x1bc04000
	s_mov_b64 s[28:29], 0x12c0c000
	s_mov_b64 s[30:31], 0x12c0c400
	s_mov_b64 s[34:35], 0x1bc06000
	s_mov_b64 s[36:37], 0x8000
	s_movk_i32 s47, 0x1000
	s_movk_i32 s48, 0x5000
	s_mov_b32 s49, 0x8000
	s_mov_b32 s54, 0x9000
	s_mov_b32 s55, 0xd000
	s_branch .LBB0_1591

; #define SBAR() __builtin_amdgcn_sched_barrier(0)
; #define ROT() do { const int t_ = bv; bv = bk; bk = bw; bw = t_; } while (0)
; __device__ __forceinline__ void finishSM(f32x16& p0, f32x16& p1, float& l_reg, bf16x8& pa0, bf16x8& pa1, bf16x8& pa2, bf16x8& pa3) {
; #pragma unroll
;   for (int r = 0; r < 16; ++r) p1[r] = __builtin_amdgcn_exp2f(p1[r]);
;   float ps = 0;
; #pragma unroll
;   for (int r = 0; r < 16; ++r) ps += p0[r];
; #pragma unroll
;   for (int r = 0; r < 16; ++r) ps += p1[r];
;   l_reg += ps;
;     ...
;   PK4(p0, 0, pa0); PK4(p0, 8, pa1); PK4(p1, 0, pa2); PK4(p1, 8, pa3);
;     ...
; }
; template <bool SHIFT> __device__ __forceinline__ void attn_dense_body(const bf16* __restrict__ Qb, const bf16* __restrict__ Kh, const bf16* __restrict__ Vh, bf16* __restrict__ Ob, int seq, char* lds, LAS unsigned char* ldsl, float negB, const float* __restrict__ gq, int qpos0) {
;     ...
;     DMA(bw, (j + 1) * KVBLK);
;     SBAR(); qkt<SHIFT ? 7 : 6>(pB0, pB1, (bf16*)((char*)K_lds + bk * SHM_K), qr, r32, hi);
;     finishSM(pA0, pA1, l_reg, pa0, pa1, pa2, pa3); SBAR();
;     pv_d0(o, vb0 + bv * (int)SHM_V, pa0, pa1, pa2, pa3); partialSM(pB0);
;     asm volatile("s_waitcnt vmcnt(0)" ::: "memory"); __syncthreads(); ROT();
.LBB0_1595:
	s_mov_b32 s58, s59
	s_lshl_b32 s59, s59, 14
	s_add_i32 s60, s59, 0
	v_lshl_add_u64 v[140:141], s[10:11], 0, v[134:135]
	s_add_i32 s61, s60, s4
	v_lshl_add_u64 v[48:49], v[140:141], 0, s[22:23]
	s_add_i32 m0, s61, 0xc000
	v_lshl_add_u64 v[142:143], s[10:11], 0, v[136:137]
	global_load_lds_dwordx4 v[48:49], off
	v_lshl_add_u64 v[48:49], v[142:143], 0, s[24:25]
	s_add_i32 m0, s61, 0xc400
	v_lshl_add_u64 v[144:145], s[10:11], 0, v[138:139]
	global_load_lds_dwordx4 v[48:49], off
	v_lshl_add_u64 v[48:49], v[144:145], 0, s[26:27]
	s_add_i32 m0, s5, s59
	s_nop 0
	global_load_lds_dwordx4 v[48:49], off
	s_lshl_b32 s59, s33, 14
	s_add_i32 s61, s59, 0
	v_add_u32_e32 v52, s61, v146
	ds_read_b128 v[48:51], v52 offset:49152
	ds_read_b128 v[52:55], v52 offset:57344
	v_add_u32_e32 v184, s61, v148
	v_add_u32_e32 v189, s61, v149
	v_add_u32_e32 v202, s61, v150
	s_waitcnt lgkmcnt(0)
	v_mfma_f32_32x32x16_bf16 v[64:79], v[48:51], v[86:89], 0
	v_add_u32_e32 v48, s61, v147
	ds_read_b128 v[172:175], v48 offset:49152
	ds_read_b128 v[176:179], v48 offset:57344
	ds_read_b128 v[180:183], v184 offset:49152
	ds_read_b128 v[184:187], v184 offset:57344
	ds_read_b128 v[190:193], v189 offset:49152
	ds_read_b128 v[194:197], v189 offset:57344
	ds_read_b128 v[198:201], v202 offset:49152
	ds_read_b128 v[202:205], v202 offset:57344
	v_exp_f32_e32 v189, v32
	v_add_f32_e32 v32, 0, v169
	v_add_f32_e32 v32, v171, v32
	v_add_f32_e32 v32, v166, v32
	v_mfma_f32_32x32x16_bf16 v[48:63], v[52:55], v[86:89], 0
	v_add_f32_e32 v32, v170, v32
	v_add_f32_e32 v32, v165, v32
	v_add_f32_e32 v32, v168, v32
	v_add_f32_e32 v32, v164, v32
	v_add_f32_e32 v32, v167, v32
	v_add_f32_e32 v32, v161, v32
	v_add_f32_e32 v32, v163, v32
	s_waitcnt lgkmcnt(0)
	v_mfma_f32_32x32x16_bf16 v[64:79], v[172:175], v[82:85], v[64:79]
	v_add_f32_e32 v32, v158, v32
	v_add_f32_e32 v32, v162, v32
	v_add_f32_e32 v32, v157, v32
	v_exp_f32_e32 v210, v33
	v_add_f32_e32 v32, v160, v32
	v_exp_f32_e32 v211, v34
	v_add_f32_e32 v32, v156, v32
	v_mfma_f32_32x32x16_bf16 v[48:63], v[176:179], v[82:85], v[48:63]
	v_exp_f32_e32 v212, v35
	v_add_f32_e32 v32, v159, v32
	v_exp_f32_e32 v213, v36
	v_add_f32_e32 v32, v189, v32
	v_exp_f32_e32 v214, v37
	v_add_f32_e32 v32, v210, v32
	v_exp_f32_e32 v176, v38
	v_mfma_f32_32x32x16_bf16 v[64:79], v[180:183], v[90:93], v[64:79]
	v_add_f32_e32 v32, v211, v32
	v_exp_f32_e32 v177, v39
	v_add_f32_e32 v32, v212, v32
	v_exp_f32_e32 v178, v40
	v_add_f32_e32 v32, v213, v32
	v_exp_f32_e32 v179, v41
	v_add_f32_e32 v32, v214, v32
	v_mfma_f32_32x32x16_bf16 v[48:63], v[184:187], v[90:93], v[48:63]
	v_exp_f32_e32 v215, v42
	v_add_f32_e32 v32, v176, v32
	v_exp_f32_e32 v216, v43
	v_add_f32_e32 v32, v177, v32
	v_exp_f32_e32 v217, v44
	v_add_f32_e32 v32, v178, v32
	v_exp_f32_e32 v180, v45
	v_mfma_f32_32x32x16_bf16 v[64:79], v[190:193], v[94:97], v[64:79]
	v_add_f32_e32 v32, v179, v32
	v_exp_f32_e32 v181, v46
	v_add_f32_e32 v32, v215, v32
	v_exp_f32_e32 v47, v47
	v_add_f32_e32 v32, v216, v32
	v_add_u32_e32 v206, s61, v151
	v_add_f32_e32 v32, v217, v32
	v_mfma_f32_32x32x16_bf16 v[48:63], v[194:197], v[94:97], v[48:63]
	ds_read_b128 v[172:175], v206 offset:49152
	ds_read_b128 v[206:209], v206 offset:57344
	v_add_f32_e32 v32, v180, v32
	v_add_f32_e32 v32, v181, v32
	v_add_f32_e32 v32, v47, v32
	v_add_f32_e32 v133, v133, v32
	v_cvt_pk_bf16_f32 v32, v169, v171
	v_cvt_pk_bf16_f32 v33, v166, v170
	v_mfma_f32_32x32x16_bf16 v[64:79], v[198:201], v[98:101], v[64:79]
	v_cvt_pk_bf16_f32 v34, v165, v168
	v_cvt_pk_bf16_f32 v35, v164, v167
	v_cvt_pk_bf16_f32 v36, v161, v163
	v_cvt_pk_bf16_f32 v37, v158, v162
	v_cvt_pk_bf16_f32 v38, v157, v160
	v_cvt_pk_bf16_f32 v39, v156, v159
	v_cvt_pk_bf16_f32 v40, v189, v210
	v_mfma_f32_32x32x16_bf16 v[48:63], v[202:205], v[98:101], v[48:63]
	v_cvt_pk_bf16_f32 v41, v211, v212
	v_cvt_pk_bf16_f32 v42, v213, v214
	v_cvt_pk_bf16_f32 v43, v176, v177
	v_cvt_pk_bf16_f32 v44, v178, v179
	v_cvt_pk_bf16_f32 v45, v215, v216
	v_cvt_pk_bf16_f32 v46, v217, v180
	v_cvt_pk_bf16_f32 v47, v181, v47
	s_waitcnt lgkmcnt(0)
	v_mfma_f32_32x32x16_bf16 v[64:79], v[172:175], v[102:105], v[64:79]
	v_mfma_f32_32x32x16_bf16 v[48:63], v[206:209], v[102:105], v[48:63]
	s_lshl_b32 s61, s56, 14
	v_add_u32_e32 v176, s61, v115
	ds_read_b64_tr_b16 v[156:157], v176 offset:0
	ds_read_b64_tr_b16 v[158:159], v176 offset:0x800
	ds_read_b64_tr_b16 v[160:161], v176 offset:0x1000
	ds_read_b64_tr_b16 v[162:163], v176 offset:0x1800
	ds_read_b64_tr_b16 v[164:165], v176 offset:0x2000
	ds_read_b64_tr_b16 v[166:167], v176 offset:0x2800
	ds_read_b64_tr_b16 v[168:169], v176 offset:0x3000
	ds_read_b64_tr_b16 v[170:171], v176 offset:0x3800
	s_waitcnt lgkmcnt(0)
	s_nop 0
	v_mfma_f32_32x32x16_bf16 v[0:15], v[32:35], v[156:159], v[0:15]
	ds_read_b64_tr_b16 v[156:157], v176 offset:0x200
	ds_read_b64_tr_b16 v[158:159], v176 offset:0xa00
	v_mfma_f32_32x32x16_bf16 v[0:15], v[36:39], v[160:163], v[0:15]
	ds_read_b64_tr_b16 v[160:161], v176 offset:0x1200
	ds_read_b64_tr_b16 v[162:163], v176 offset:0x1a00
	v_mfma_f32_32x32x16_bf16 v[0:15], v[40:43], v[164:167], v[0:15]
	ds_read_b64_tr_b16 v[164:165], v176 offset:0x2200
	ds_read_b64_tr_b16 v[166:167], v176 offset:0x2a00
	ds_read_b64_tr_b16 v[172:173], v176 offset:0x3200
	ds_read_b64_tr_b16 v[174:175], v176 offset:0x3a00
	s_waitcnt lgkmcnt(0)
	v_mfma_f32_32x32x16_bf16 v[0:15], v[44:47], v[168:171], v[0:15]
	s_add_i32 s61, s5, s61
	v_lshl_add_u64 v[140:141], v[140:141], 0, s[28:29]
	s_add_i32 m0, s61, 0xc000
	s_waitcnt vmcnt(0)
	s_waitcnt vmcnt(0)
	s_barrier
; #define SBAR() __builtin_amdgcn_sched_barrier(0)
; #define ROT() do { const int t_ = bv; bv = bk; bk = bw; bw = t_; } while (0)
; template <int D0> __device__ __forceinline__ void pv_one(f32x16& od, int vb, bf16x8 pa0, bf16x8 pa1, bf16x8 pa2, bf16x8 pa3) {
;   const s16x4 l0 = tr_read<v_rd_off(D0, 0, 0)>(vb), h0 = tr_read<v_rd_off(D0, 0, 1)>(vb), l1 = tr_read<v_rd_off(D0, 1, 0)>(vb), h1 = tr_read<v_rd_off(D0, 1, 1)>(vb);
;   const s16x4 l2 = tr_read<v_rd_off(D0, 2, 0)>(vb), h2 = tr_read<v_rd_off(D0, 2, 1)>(vb), l3 = tr_read<v_rd_off(D0, 3, 0)>(vb), h3 = tr_read<v_rd_off(D0, 3, 1)>(vb);
;   asm volatile("s_waitcnt lgkmcnt(0)" ::: "memory"); SBAR();
;     ...
;   od = __builtin_amdgcn_mfma_f32_32x32x16_bf16(pa0, PK(l0, h0), od, 0, 0, 0);
;   od = __builtin_amdgcn_mfma_f32_32x32x16_bf16(pa1, PK(l1, h1), od, 0, 0, 0);
;   od = __builtin_amdgcn_mfma_f32_32x32x16_bf16(pa2, PK(l2, h2), od, 0, 0, 0);
;   od = __builtin_amdgcn_mfma_f32_32x32x16_bf16(pa3, PK(l3, h3), od, 0, 0, 0);
;     ...
; }
; __device__ __forceinline__ void pv_d0(f32x16* o, int vb, bf16x8 pa0, bf16x8 pa1, bf16x8 pa2, bf16x8 pa3) {
;   pv_one<0>(o[0], vb, pa0, pa1, pa2, pa3); pv_one<1>(o[1], vb, pa0, pa1, pa2, pa3);
; template <bool SHIFT> __device__ __forceinline__ void attn_dense_body(const bf16* __restrict__ Qb, const bf16* __restrict__ Kh, const bf16* __restrict__ Vh, bf16* __restrict__ Ob, int seq, char* lds, LAS unsigned char* ldsl, float negB, const float* __restrict__ gq, int qpos0) {
;     ...
;     DMA(bw, (j + 2) * KVBLK);
;     SBAR(); qkt<SHIFT ? 7 : 6>(pA0, pA1, (bf16*)((char*)K_lds + bk * SHM_K), qr, r32, hi);
;     finishSM(pB0, pB1, l_reg, pa0, pa1, pa2, pa3); SBAR();
;     pv_d0(o, vb0 + bv * (int)SHM_V, pa0, pa1, pa2, pa3); partialSM(pA0);
;     asm volatile("s_waitcnt vmcnt(0)" ::: "memory"); __syncthreads(); ROT();
	v_mfma_f32_32x32x16_bf16 v[16:31], v[32:35], v[156:159], v[16:31]
	global_load_lds_dwordx4 v[140:141], off
	v_lshl_add_u64 v[32:33], v[142:143], 0, s[30:31]
	s_add_i32 m0, s61, 0xc400
	v_exp_f32_e32 v189, v66
	global_load_lds_dwordx4 v[32:33], off
	v_lshl_add_u64 v[32:33], v[144:145], 0, s[34:35]
	s_mov_b32 m0, s61
	v_mfma_f32_32x32x16_bf16 v[16:31], v[36:39], v[160:163], v[16:31]
	global_load_lds_dwordx4 v[32:33], off
	v_exp_f32_e32 v144, v64
	v_exp_f32_e32 v145, v65
	v_exp_f32_e32 v194, v67
	v_exp_f32_e32 v195, v68
	v_exp_f32_e32 v196, v69
	v_mfma_f32_32x32x16_bf16 v[16:31], v[40:43], v[164:167], v[16:31]
	v_exp_f32_e32 v197, v70
	v_exp_f32_e32 v198, v71
	v_exp_f32_e32 v199, v72
	v_exp_f32_e32 v200, v73
	v_exp_f32_e32 v201, v74
	v_exp_f32_e32 v202, v75
	v_exp_f32_e32 v203, v76
	v_mfma_f32_32x32x16_bf16 v[16:31], v[44:47], v[172:175], v[16:31]
	v_exp_f32_e32 v204, v77
	v_exp_f32_e32 v205, v78
	v_exp_f32_e32 v206, v79
	v_add_u32_e32 v36, s60, v146
	ds_read_b128 v[32:35], v36 offset:49152
	ds_read_b128 v[36:39], v36 offset:57344
	v_add_u32_e32 v40, s60, v147
	v_add_u32_e32 v41, s60, v148
	v_add_u32_e32 v42, s60, v149
	ds_read_b128 v[140:143], v40 offset:49152
	ds_read_b128 v[156:159], v40 offset:57344
	ds_read_b128 v[160:163], v41 offset:49152
	ds_read_b128 v[164:167], v41 offset:57344
	ds_read_b128 v[168:171], v42 offset:49152
	ds_read_b128 v[172:175], v42 offset:57344
	v_exp_f32_e32 v207, v48
	v_add_f32_e32 v48, 0, v144
	v_add_f32_e32 v48, v145, v48
	s_waitcnt lgkmcnt(0)
	v_mfma_f32_32x32x16_bf16 v[64:79], v[32:35], v[86:89], 0
	v_add_f32_e32 v48, v189, v48
	v_add_f32_e32 v48, v194, v48
	v_add_f32_e32 v48, v195, v48
	v_add_f32_e32 v48, v196, v48
	v_add_f32_e32 v48, v197, v48
	v_add_f32_e32 v48, v198, v48
	v_add_f32_e32 v48, v199, v48
	v_mfma_f32_32x32x16_bf16 v[32:47], v[36:39], v[86:89], 0
	v_add_f32_e32 v48, v200, v48
	v_add_f32_e32 v48, v201, v48
	v_add_u32_e32 v180, s60, v150
	v_add_f32_e32 v48, v202, v48
	ds_read_b128 v[176:179], v180 offset:49152
	ds_read_b128 v[180:183], v180 offset:57344
	v_add_f32_e32 v48, v203, v48
	v_exp_f32_e32 v208, v49
	v_mfma_f32_32x32x16_bf16 v[32:47], v[156:159], v[82:85], v[32:47]
	v_add_f32_e32 v48, v204, v48
	v_add_f32_e32 v48, v205, v48
	v_add_f32_e32 v48, v206, v48
	v_add_f32_e32 v48, v207, v48
	v_add_f32_e32 v48, v208, v48
	v_exp_f32_e32 v209, v54
	v_add_u32_e32 v190, s60, v151
	v_mfma_f32_32x32x16_bf16 v[64:79], v[140:143], v[82:85], v[64:79]
	v_exp_f32_e32 v140, v50
	v_exp_f32_e32 v141, v51
	v_exp_f32_e32 v142, v52
	v_exp_f32_e32 v143, v53
	v_add_f32_e32 v48, v140, v48
	v_exp_f32_e32 v210, v55
	v_add_f32_e32 v48, v141, v48
	v_mfma_f32_32x32x16_bf16 v[32:47], v[164:167], v[90:93], v[32:47]
	ds_read_b128 v[184:187], v190 offset:49152
	ds_read_b128 v[190:193], v190 offset:57344
	v_exp_f32_e32 v211, v56
	v_add_f32_e32 v48, v142, v48
	v_exp_f32_e32 v156, v57
	v_add_f32_e32 v48, v143, v48
	v_exp_f32_e32 v157, v58
	v_add_f32_e32 v48, v209, v48
	v_mfma_f32_32x32x16_bf16 v[64:79], v[160:163], v[90:93], v[64:79]
	v_exp_f32_e32 v158, v59
	v_add_f32_e32 v48, v210, v48
	v_exp_f32_e32 v159, v60
	v_add_f32_e32 v48, v211, v48
	v_exp_f32_e32 v212, v61
	v_add_f32_e32 v48, v156, v48
	v_exp_f32_e32 v213, v62
	v_mfma_f32_32x32x16_bf16 v[32:47], v[172:175], v[94:97], v[32:47]
	v_add_f32_e32 v48, v157, v48
	v_exp_f32_e32 v63, v63
	v_add_f32_e32 v48, v158, v48
	v_add_f32_e32 v48, v159, v48
	v_add_f32_e32 v48, v212, v48
	v_add_f32_e32 v48, v213, v48
	v_add_f32_e32 v48, v63, v48
	v_mfma_f32_32x32x16_bf16 v[64:79], v[168:171], v[94:97], v[64:79]
	v_add_f32_e32 v133, v133, v48
	v_cvt_pk_bf16_f32 v48, v144, v145
	v_cvt_pk_bf16_f32 v49, v189, v194
	v_cvt_pk_bf16_f32 v50, v195, v196
	v_cvt_pk_bf16_f32 v51, v197, v198
	v_cvt_pk_bf16_f32 v52, v199, v200
	v_cvt_pk_bf16_f32 v53, v201, v202
	s_waitcnt lgkmcnt(0)
	v_mfma_f32_32x32x16_bf16 v[32:47], v[180:183], v[98:101], v[32:47]
	v_cvt_pk_bf16_f32 v54, v203, v204
	v_cvt_pk_bf16_f32 v55, v205, v206
	v_cvt_pk_bf16_f32 v56, v207, v208
	v_cvt_pk_bf16_f32 v57, v140, v141
	v_cvt_pk_bf16_f32 v58, v142, v143
	v_cvt_pk_bf16_f32 v59, v209, v210
	v_cvt_pk_bf16_f32 v60, v211, v156
	v_mfma_f32_32x32x16_bf16 v[64:79], v[176:179], v[98:101], v[64:79]
	v_cvt_pk_bf16_f32 v61, v157, v158
	v_cvt_pk_bf16_f32 v62, v159, v212
	v_cvt_pk_bf16_f32 v63, v213, v63
	v_mfma_f32_32x32x16_bf16 v[32:47], v[190:193], v[102:105], v[32:47]
	v_mfma_f32_32x32x16_bf16 v[64:79], v[184:187], v[102:105], v[64:79]
	v_add_u32_e32 v144, s59, v115
	ds_read_b64_tr_b16 v[140:141], v144 offset:0
	ds_read_b64_tr_b16 v[142:143], v144 offset:0x800
	ds_read_b64_tr_b16 v[156:157], v144 offset:0x1000
	ds_read_b64_tr_b16 v[158:159], v144 offset:0x1800
	ds_read_b64_tr_b16 v[160:161], v144 offset:0x2000
	ds_read_b64_tr_b16 v[162:163], v144 offset:0x2800
	ds_read_b64_tr_b16 v[164:165], v144 offset:0x3000
	ds_read_b64_tr_b16 v[166:167], v144 offset:0x3800
	s_waitcnt lgkmcnt(0)
	s_nop 0
	v_mfma_f32_32x32x16_bf16 v[0:15], v[48:51], v[140:143], v[0:15]
	ds_read_b64_tr_b16 v[140:141], v144 offset:0x200
	ds_read_b64_tr_b16 v[142:143], v144 offset:0xa00
	v_mfma_f32_32x32x16_bf16 v[0:15], v[52:55], v[156:159], v[0:15]
	ds_read_b64_tr_b16 v[156:157], v144 offset:0x1200
	ds_read_b64_tr_b16 v[158:159], v144 offset:0x1a00
	ds_read_b64_tr_b16 v[172:173], v144 offset:0x2200
	ds_read_b64_tr_b16 v[174:175], v144 offset:0x2a00
	ds_read_b64_tr_b16 v[176:177], v144 offset:0x3200
	ds_read_b64_tr_b16 v[178:179], v144 offset:0x3a00
	s_waitcnt lgkmcnt(0)
	v_mfma_f32_32x32x16_bf16 v[0:15], v[56:59], v[160:163], v[0:15]
	v_mfma_f32_32x32x16_bf16 v[0:15], v[60:63], v[164:167], v[0:15]
	v_mfma_f32_32x32x16_bf16 v[16:31], v[48:51], v[140:143], v[16:31]
	s_nop 2
	v_exp_f32_e32 v169, v64
	v_exp_f32_e32 v171, v65
	v_exp_f32_e32 v166, v66
	v_exp_f32_e32 v170, v67
	v_exp_f32_e32 v165, v68
	v_exp_f32_e32 v168, v69
	v_exp_f32_e32 v164, v70
	v_mfma_f32_32x32x16_bf16 v[16:31], v[52:55], v[156:159], v[16:31]
	v_exp_f32_e32 v167, v71
	v_exp_f32_e32 v161, v72
	v_exp_f32_e32 v163, v73
	v_exp_f32_e32 v158, v74
	v_exp_f32_e32 v162, v75
	v_exp_f32_e32 v157, v76
	v_exp_f32_e32 v160, v77
	v_mfma_f32_32x32x16_bf16 v[16:31], v[56:59], v[172:175], v[16:31]
	v_exp_f32_e32 v156, v78
	v_exp_f32_e32 v159, v79
	s_waitcnt vmcnt(0)
	s_add_i32 s57, s57, 2
	v_lshl_add_u64 v[134:135], v[134:135], 0, s[36:37]
	v_lshl_add_u64 v[136:137], v[136:137], 0, s[36:37]
	v_lshl_add_u64 v[138:139], v[138:139], 0, s[16:17]
	v_mfma_f32_32x32x16_bf16 v[16:31], v[60:63], v[176:179], v[16:31]
	s_mov_b32 s59, s33
	s_mov_b32 s33, s56
	s_cmp_gt_u32 s57, 64
	s_mov_b32 s56, s58
	s_waitcnt vmcnt(0)
	s_barrier
; #define SBAR() __builtin_amdgcn_sched_barrier(0)
; #define ROT() do { const int t_ = bv; bv = bk; bk = bw; bw = t_; } while (0)
; __device__ __forceinline__ void finishSM(f32x16& p0, f32x16& p1, float& l_reg, bf16x8& pa0, bf16x8& pa1, bf16x8& pa2, bf16x8& pa3) {
; #pragma unroll
;   for (int r = 0; r < 16; ++r) p1[r] = __builtin_amdgcn_exp2f(p1[r]);
;   float ps = 0;
; #pragma unroll
;   for (int r = 0; r < 16; ++r) ps += p0[r];
; #pragma unroll
;   for (int r = 0; r < 16; ++r) ps += p1[r];
;   l_reg += ps;
;     ...
;   PK4(p0, 0, pa0); PK4(p0, 8, pa1); PK4(p1, 0, pa2); PK4(p1, 8, pa3);
;     ...
; }
; template <bool SHIFT> __device__ __forceinline__ void attn_dense_body(const bf16* __restrict__ Qb, const bf16* __restrict__ Kh, const bf16* __restrict__ Vh, bf16* __restrict__ Ob, int seq, char* lds, LAS unsigned char* ldsl, float negB, const float* __restrict__ gq, int qpos0) {
;     ...
;   SBAR(); qkt<SHIFT ? 7 : 6>(pB0, pB1, (bf16*)((char*)K_lds + bk * SHM_K), qr, r32, hi);
;   finishSM(pA0, pA1, l_reg, pa0, pa1, pa2, pa3); SBAR();
;   pv_d0(o, vb0 + bv * (int)SHM_V, pa0, pa1, pa2, pa3); partialSM(pB0);
;   ROT();
;   finishSM(pB0, pB1, l_reg, pa0, pa1, pa2, pa3); SBAR();
	s_cbranch_scc0 .LBB0_1595
	s_add_i32 s4, 0, 0x10000
	v_add_u32_e32 v52, s4, v146
	ds_read_b128 v[48:51], v52
	ds_read_b128 v[52:55], v52 offset:8192
	v_add_u32_e32 v176, s4, v149
	v_add_u32_e32 v184, s4, v150
	v_add_u32_e32 v189, s4, v151
	s_waitcnt lgkmcnt(1)
	v_mfma_f32_32x32x16_bf16 v[64:79], v[48:51], v[86:89], 0
	v_add_u32_e32 v48, s4, v147
	v_add_u32_e32 v49, s4, v148
	ds_read_b128 v[134:137], v48
	ds_read_b128 v[138:141], v48 offset:8192
	ds_read_b128 v[142:145], v49
	ds_read_b128 v[172:175], v49 offset:8192
	v_exp_f32_e32 v194, v33
	v_exp_f32_e32 v195, v34
	v_exp_f32_e32 v196, v35
	v_exp_f32_e32 v197, v36
	s_waitcnt lgkmcnt(4)
	v_mfma_f32_32x32x16_bf16 v[48:63], v[52:55], v[86:89], 0
	ds_read_b128 v[86:89], v176
	ds_read_b128 v[176:179], v176 offset:8192
	ds_read_b128 v[180:183], v184
	ds_read_b128 v[184:187], v184 offset:8192
	v_exp_f32_e32 v198, v37
	v_exp_f32_e32 v47, v47
	s_waitcnt lgkmcnt(7)
	v_mfma_f32_32x32x16_bf16 v[64:79], v[134:137], v[82:85], v[64:79]
	ds_read_b128 v[134:137], v189
	ds_read_b128 v[190:193], v189 offset:8192
	v_exp_f32_e32 v189, v32
	v_add_f32_e32 v32, 0, v169
	v_add_f32_e32 v32, v171, v32
	v_add_f32_e32 v32, v166, v32
	v_add_f32_e32 v32, v170, v32
	v_add_f32_e32 v32, v165, v32
	s_waitcnt lgkmcnt(8)
	v_mfma_f32_32x32x16_bf16 v[48:63], v[138:141], v[82:85], v[48:63]
	v_add_f32_e32 v32, v168, v32
	v_add_f32_e32 v32, v164, v32
	v_add_f32_e32 v32, v167, v32
	v_add_f32_e32 v32, v161, v32
	v_add_f32_e32 v32, v163, v32
	v_add_f32_e32 v32, v158, v32
	v_add_f32_e32 v32, v162, v32
	s_waitcnt lgkmcnt(7)
	v_mfma_f32_32x32x16_bf16 v[64:79], v[142:145], v[90:93], v[64:79]
	v_add_f32_e32 v32, v157, v32
	v_add_f32_e32 v32, v160, v32
	v_add_f32_e32 v32, v156, v32
	v_add_f32_e32 v32, v159, v32
	v_add_f32_e32 v32, v189, v32
	v_add_f32_e32 v32, v194, v32
	v_exp_f32_e32 v82, v38
	s_waitcnt lgkmcnt(6)
	v_mfma_f32_32x32x16_bf16 v[48:63], v[172:175], v[90:93], v[48:63]
	v_add_f32_e32 v32, v195, v32
	v_exp_f32_e32 v83, v39
	v_add_f32_e32 v32, v196, v32
	v_exp_f32_e32 v84, v40
	v_add_f32_e32 v32, v197, v32
	v_exp_f32_e32 v85, v41
	v_add_f32_e32 v32, v198, v32
	s_waitcnt lgkmcnt(5)
	v_mfma_f32_32x32x16_bf16 v[64:79], v[86:89], v[94:97], v[64:79]
	v_exp_f32_e32 v138, v42
	v_add_f32_e32 v32, v82, v32
	v_exp_f32_e32 v139, v43
	v_add_f32_e32 v32, v83, v32
	v_exp_f32_e32 v140, v44
	v_add_f32_e32 v32, v84, v32
	v_exp_f32_e32 v141, v45
	s_waitcnt lgkmcnt(4)
	v_mfma_f32_32x32x16_bf16 v[48:63], v[176:179], v[94:97], v[48:63]
	v_add_f32_e32 v32, v85, v32
	v_exp_f32_e32 v142, v46
	v_add_f32_e32 v32, v138, v32
	v_add_f32_e32 v32, v139, v32
	v_add_f32_e32 v32, v140, v32
	v_add_f32_e32 v32, v141, v32
	v_add_f32_e32 v32, v142, v32
	s_waitcnt lgkmcnt(3)
	v_mfma_f32_32x32x16_bf16 v[64:79], v[180:183], v[98:101], v[64:79]
	v_add_f32_e32 v32, v47, v32
	v_add_f32_e32 v133, v133, v32
	v_cvt_pk_bf16_f32 v32, v169, v171
	v_cvt_pk_bf16_f32 v33, v166, v170
	v_cvt_pk_bf16_f32 v34, v165, v168
	v_cvt_pk_bf16_f32 v35, v164, v167
	v_cvt_pk_bf16_f32 v36, v161, v163
	s_waitcnt lgkmcnt(2)
	v_mfma_f32_32x32x16_bf16 v[48:63], v[184:187], v[98:101], v[48:63]
	v_cvt_pk_bf16_f32 v37, v158, v162
	v_cvt_pk_bf16_f32 v38, v157, v160
	v_cvt_pk_bf16_f32 v39, v156, v159
	v_cvt_pk_bf16_f32 v40, v189, v194
	v_cvt_pk_bf16_f32 v41, v195, v196
	v_cvt_pk_bf16_f32 v42, v197, v198
	v_cvt_pk_bf16_f32 v43, v82, v83
	v_cvt_pk_bf16_f32 v44, v84, v85
	v_cvt_pk_bf16_f32 v45, v138, v139
	v_cvt_pk_bf16_f32 v46, v140, v141
	v_cvt_pk_bf16_f32 v47, v142, v47
	s_waitcnt lgkmcnt(1)
	v_mfma_f32_32x32x16_bf16 v[64:79], v[134:137], v[102:105], v[64:79]
	s_waitcnt lgkmcnt(0)
	v_mfma_f32_32x32x16_bf16 v[48:63], v[190:193], v[102:105], v[48:63]
	ds_read_b64_tr_b16 v[82:83], v115 offset:0
	ds_read_b64_tr_b16 v[84:85], v115 offset:0x800
	ds_read_b64_tr_b16 v[86:87], v115 offset:0x1000
	ds_read_b64_tr_b16 v[88:89], v115 offset:0x1800
	ds_read_b64_tr_b16 v[90:91], v115 offset:0x2000
	ds_read_b64_tr_b16 v[92:93], v115 offset:0x2800
	ds_read_b64_tr_b16 v[94:95], v115 offset:0x3000
	ds_read_b64_tr_b16 v[96:97], v115 offset:0x3800
	s_waitcnt lgkmcnt(0)
	s_nop 0
	v_mfma_f32_32x32x16_bf16 v[0:15], v[32:35], v[82:85], v[0:15]
	ds_read_b64_tr_b16 v[82:83], v115 offset:0x200
	ds_read_b64_tr_b16 v[84:85], v115 offset:0xa00
	v_mfma_f32_32x32x16_bf16 v[0:15], v[36:39], v[86:89], v[0:15]
	ds_read_b64_tr_b16 v[86:87], v115 offset:0x1200
	ds_read_b64_tr_b16 v[88:89], v115 offset:0x1a00
	v_mfma_f32_32x32x16_bf16 v[0:15], v[40:43], v[90:93], v[0:15]
	ds_read_b64_tr_b16 v[90:91], v115 offset:0x2200
	ds_read_b64_tr_b16 v[92:93], v115 offset:0x2a00
	ds_read_b64_tr_b16 v[98:99], v115 offset:0x3200
	ds_read_b64_tr_b16 v[100:101], v115 offset:0x3a00
	s_waitcnt lgkmcnt(0)
; #define SBAR() __builtin_amdgcn_sched_barrier(0)
; __device__ __forceinline__ int crow(int r, int hi) { return (r & 3) + 8 * (r >> 2) + 4 * hi; }
; #define ROT() do { const int t_ = bv; bv = bk; bk = bw; bw = t_; } while (0)
; template <bool SHIFT> __device__ __forceinline__ void attn_dense_body(const bf16* __restrict__ Qb, const bf16* __restrict__ Kh, const bf16* __restrict__ Vh, bf16* __restrict__ Ob, int seq, char* lds, LAS unsigned char* ldsl, float negB, const float* __restrict__ gq, int qpos0) {
;     ...
;   pv_d0(o, vb0 + bv * (int)SHM_V, pa0, pa1, pa2, pa3); partialSM(pB0);
;   ROT();
;   finishSM(pB0, pB1, l_reg, pa0, pa1, pa2, pa3); SBAR();
;   pv_d0(o, vb0 + bv * (int)SHM_V, pa0, pa1, pa2, pa3);
;     ...
;   { auto rr = __builtin_amdgcn_permlane32_swap(__float_as_uint(l_reg), __float_as_uint(l_reg), false, false); l_reg = __uint_as_float(rr[0]) + __uint_as_float(rr[1]); }
;   if (hi == 0) li_l[r32] = l_reg; asm volatile("s_waitcnt lgkmcnt(0)" ::: "memory");
;   float rli[16];
; #pragma unroll
;   for (int r = 0; r < 16; ++r) rli[r] = __builtin_amdgcn_rcpf(li_l[crow(r, hi)]);
	v_mfma_f32_32x32x16_bf16 v[0:15], v[44:47], v[94:97], v[0:15]
	v_exp_f32_e32 v64, v64
	v_exp_f32_e32 v65, v65
	v_exp_f32_e32 v66, v66
	v_exp_f32_e32 v67, v67
	v_mfma_f32_32x32x16_bf16 v[16:31], v[32:35], v[82:85], v[16:31]
	v_exp_f32_e32 v68, v68
	v_add_f32_e32 v32, 0, v64
	v_exp_f32_e32 v69, v69
	v_add_f32_e32 v32, v65, v32
	v_exp_f32_e32 v33, v70
	v_add_f32_e32 v32, v66, v32
	v_exp_f32_e32 v70, v71
	v_add_f32_e32 v32, v67, v32
	v_exp_f32_e32 v71, v72
	v_add_f32_e32 v32, v68, v32
	v_exp_f32_e32 v72, v73
	v_add_f32_e32 v32, v69, v32
	v_exp_f32_e32 v73, v74
	v_add_f32_e32 v32, v33, v32
	v_exp_f32_e32 v74, v75
	v_mfma_f32_32x32x16_bf16 v[16:31], v[36:39], v[86:89], v[16:31]
	v_add_f32_e32 v32, v70, v32
	v_exp_f32_e32 v75, v76
	v_add_f32_e32 v32, v71, v32
	v_exp_f32_e32 v76, v77
	v_add_f32_e32 v32, v72, v32
	v_exp_f32_e32 v77, v78
	v_add_f32_e32 v32, v73, v32
	v_exp_f32_e32 v78, v79
	v_add_f32_e32 v32, v74, v32
	v_exp_f32_e32 v48, v48
	v_add_f32_e32 v32, v75, v32
	v_exp_f32_e32 v49, v49
	v_add_f32_e32 v32, v76, v32
	v_exp_f32_e32 v50, v50
	v_add_f32_e32 v32, v77, v32
	v_exp_f32_e32 v51, v51
	v_mfma_f32_32x32x16_bf16 v[16:31], v[40:43], v[90:93], v[16:31]
	v_add_f32_e32 v32, v78, v32
	v_exp_f32_e32 v52, v52
	v_add_f32_e32 v32, v48, v32
	v_exp_f32_e32 v53, v53
	v_add_f32_e32 v32, v49, v32
	v_exp_f32_e32 v54, v54
	v_add_f32_e32 v32, v50, v32
	v_exp_f32_e32 v55, v55
	v_add_f32_e32 v32, v51, v32
	v_exp_f32_e32 v56, v56
	v_add_f32_e32 v32, v52, v32
	v_exp_f32_e32 v57, v57
	v_add_f32_e32 v32, v53, v32
	v_exp_f32_e32 v58, v58
	v_add_f32_e32 v32, v54, v32
	v_mfma_f32_32x32x16_bf16 v[16:31], v[44:47], v[98:101], v[16:31]
	v_exp_f32_e32 v47, v59
	v_add_f32_e32 v32, v55, v32
	v_exp_f32_e32 v59, v60
	v_add_f32_e32 v32, v56, v32
	v_exp_f32_e32 v60, v61
	v_add_f32_e32 v32, v57, v32
	v_exp_f32_e32 v61, v62
	v_add_f32_e32 v32, v58, v32
	v_exp_f32_e32 v62, v63
	v_add_f32_e32 v32, v47, v32
	v_add_f32_e32 v32, v59, v32
	v_add_f32_e32 v32, v60, v32
	v_add_f32_e32 v32, v61, v32
	v_add_f32_e32 v32, v62, v32
	v_add_f32_e32 v32, v133, v32
	v_cvt_pk_bf16_f32 v34, v64, v65
	v_cvt_pk_bf16_f32 v35, v66, v67
	v_cvt_pk_bf16_f32 v36, v68, v69
	v_cvt_pk_bf16_f32 v37, v33, v70
	v_cvt_pk_bf16_f32 v38, v71, v72
	v_cvt_pk_bf16_f32 v39, v73, v74
	v_cvt_pk_bf16_f32 v40, v75, v76
	v_cvt_pk_bf16_f32 v41, v77, v78
	v_cvt_pk_bf16_f32 v42, v48, v49
	v_cvt_pk_bf16_f32 v43, v50, v51
	v_cvt_pk_bf16_f32 v44, v52, v53
	v_cvt_pk_bf16_f32 v45, v54, v55
	v_cvt_pk_bf16_f32 v46, v56, v57
	v_cvt_pk_bf16_f32 v47, v58, v47
	v_cvt_pk_bf16_f32 v48, v59, v60
	v_cvt_pk_bf16_f32 v49, v61, v62
	s_nop 0
	ds_read_b64_tr_b16 v[50:51], v152 offset:0
	ds_read_b64_tr_b16 v[52:53], v152 offset:0x800
	ds_read_b64_tr_b16 v[54:55], v152 offset:0x1000
	ds_read_b64_tr_b16 v[56:57], v152 offset:0x1800
	ds_read_b64_tr_b16 v[58:59], v152 offset:0x2000
	ds_read_b64_tr_b16 v[60:61], v152 offset:0x2800
	ds_read_b64_tr_b16 v[62:63], v152 offset:0x3000
	ds_read_b64_tr_b16 v[64:65], v152 offset:0x3800
	s_waitcnt lgkmcnt(0)
	s_nop 0
	v_mfma_f32_32x32x16_bf16 v[0:15], v[34:37], v[50:53], v[0:15]
	ds_read_b64_tr_b16 v[50:51], v152 offset:0x200
	ds_read_b64_tr_b16 v[52:53], v152 offset:0xa00
	v_mfma_f32_32x32x16_bf16 v[0:15], v[38:41], v[54:57], v[0:15]
	ds_read_b64_tr_b16 v[54:55], v152 offset:0x1200
	ds_read_b64_tr_b16 v[56:57], v152 offset:0x1a00
	v_mfma_f32_32x32x16_bf16 v[0:15], v[42:45], v[58:61], v[0:15]
	ds_read_b64_tr_b16 v[58:59], v152 offset:0x2200
	ds_read_b64_tr_b16 v[60:61], v152 offset:0x2a00
	ds_read_b64_tr_b16 v[66:67], v152 offset:0x3200
	ds_read_b64_tr_b16 v[68:69], v152 offset:0x3a00
	s_waitcnt lgkmcnt(0)
	v_mfma_f32_32x32x16_bf16 v[0:15], v[46:49], v[62:65], v[0:15]
	v_mfma_f32_32x32x16_bf16 v[16:31], v[34:37], v[50:53], v[16:31]
	v_mov_b32_e32 v33, v32
	s_nop 1
	v_permlane32_swap_b32_e32 v32, v33
	v_mfma_f32_32x32x16_bf16 v[16:31], v[38:41], v[54:57], v[16:31]
	v_mfma_f32_32x32x16_bf16 v[16:31], v[42:45], v[58:61], v[16:31]
	v_mfma_f32_32x32x16_bf16 v[16:31], v[46:49], v[66:69], v[16:31]
	s_and_saveexec_b64 s[4:5], s[6:7]
	v_add_f32_e32 v32, v32, v33
	ds_write_b32 v153, v32
	s_or_b64 exec, exec, s[4:5]
	s_waitcnt lgkmcnt(0)
	v_add_u32_e32 v40, v113, v117
	ds_read_b128 v[32:35], v40
	ds_read_b128 v[36:39], v40 offset:32
	s_waitcnt lgkmcnt(1)
	v_rcp_f32_e32 v41, v32
	v_rcp_f32_e32 v42, v33
	v_rcp_f32_e32 v43, v34
	v_rcp_f32_e32 v44, v35
	ds_read_b128 v[32:35], v40 offset:64
	s_waitcnt lgkmcnt(1)
	v_rcp_f32_e32 v45, v36
	v_rcp_f32_e32 v46, v37
	v_rcp_f32_e32 v47, v38
	v_rcp_f32_e32 v48, v39
	ds_read_b128 v[36:39], v40 offset:96
	s_waitcnt lgkmcnt(1)
; __device__ __forceinline__ int crow(int r, int hi) { return (r & 3) + 8 * (r >> 2) + 4 * hi; }
; __device__ __forceinline__ unsigned cvtpk(float lo, float hi) { unsigned r; asm volatile("v_cvt_pk_bf16_f32 %0, %1, %2" : "=v"(r) : "v"(lo), "v"(hi)); return r; }
; template <bool SHIFT> __device__ __forceinline__ void attn_dense_body(const bf16* __restrict__ Qb, const bf16* __restrict__ Kh, const bf16* __restrict__ Vh, bf16* __restrict__ Ob, int seq, char* lds, LAS unsigned char* ldsl, float negB, const float* __restrict__ gq, int qpos0) {
;     ...
;   if (hi == 0) li_l[r32] = l_reg; asm volatile("s_waitcnt lgkmcnt(0)" ::: "memory");
;   float rli[16];
; #pragma unroll
;   for (int r = 0; r < 16; ++r) rli[r] = __builtin_amdgcn_rcpf(li_l[crow(r, hi)]);
;   bf16* Ow = Ob + (long)(wid * QBLK) * LDO;
; #pragma unroll
;   for (int r = 0; r < 16; ++r) { int orow = crow(r, hi);
; #pragma unroll
;     for (int d0 = 0; d0 < 2; ++d0) Ow[(long)orow * LDO + d0 * 32 + r32] = (bf16)(cvtpk(o[d0][r] * rli[r], 0.f) & 0xffffu); }
;   __syncthreads();
	v_rcp_f32_e32 v40, v32
	v_rcp_f32_e32 v49, v33
	v_lshlrev_b32_e32 v32, 1, v116
	v_mov_b32_e32 v33, v81
	v_rcp_f32_e32 v50, v34
	v_rcp_f32_e32 v51, v35
	v_lshl_add_u64 v[32:33], s[38:39], 0, v[32:33]
	v_lshlrev_b32_e32 v34, 1, v108
	v_mov_b32_e32 v35, v81
	v_lshl_add_u64 v[32:33], v[32:33], 0, v[34:35]
	v_mul_f32_e32 v0, v0, v41
	v_lshl_add_u64 v[32:33], v[32:33], 0, v[118:119]
	v_cvt_pk_bf16_f32 v0, v0, v81
	global_store_short v[32:33], v0, off
	v_mul_f32_e32 v0, v16, v41
	v_cvt_pk_bf16_f32 v0, v0, v81
	global_store_short v[32:33], v0, off offset:64
	v_mul_f32_e32 v0, v1, v42
	v_cvt_pk_bf16_f32 v0, v0, v81
	global_store_short v[32:33], v0, off offset:2048
	v_mul_f32_e32 v0, v17, v42
	v_cvt_pk_bf16_f32 v0, v0, v81
	global_store_short v[32:33], v0, off offset:2112
	v_mul_f32_e32 v0, v2, v43
	v_cvt_pk_bf16_f32 v2, v0, v81
	v_add_co_u32_e32 v0, vcc, s47, v32
	s_waitcnt lgkmcnt(0)
	v_rcp_f32_e32 v36, v36
	v_addc_co_u32_e32 v1, vcc, 0, v33, vcc
	global_store_short v[0:1], v2, off
	v_mul_f32_e32 v2, v18, v43
	v_cvt_pk_bf16_f32 v2, v2, v81
	global_store_short v[0:1], v2, off offset:64
	v_mul_f32_e32 v2, v3, v44
	v_cvt_pk_bf16_f32 v2, v2, v81
	global_store_short v[0:1], v2, off offset:2048
	v_mul_f32_e32 v2, v19, v44
	v_cvt_pk_bf16_f32 v2, v2, v81
	global_store_short v[0:1], v2, off offset:2112
	v_mul_f32_e32 v0, v4, v45
	v_cvt_pk_bf16_f32 v4, v0, v81
	v_add_co_u32_e32 v0, vcc, s41, v32
	v_rcp_f32_e32 v37, v37
	s_nop 0
	v_addc_co_u32_e32 v1, vcc, 0, v33, vcc
	v_add_co_u32_e32 v2, vcc, s48, v32
	v_rcp_f32_e32 v38, v38
	s_nop 0
	v_addc_co_u32_e32 v3, vcc, 0, v33, vcc
	global_store_short v[2:3], v4, off offset:-4096
	v_mul_f32_e32 v4, v20, v45
	v_cvt_pk_bf16_f32 v4, v4, v81
	global_store_short v[0:1], v4, off offset:64
	v_mul_f32_e32 v4, v5, v46
	v_cvt_pk_bf16_f32 v4, v4, v81
	global_store_short v[0:1], v4, off offset:2048
	v_mul_f32_e32 v4, v21, v46
	v_cvt_pk_bf16_f32 v4, v4, v81
	global_store_short v[0:1], v4, off offset:2112
	v_mul_f32_e32 v0, v6, v47
	v_cvt_pk_bf16_f32 v0, v0, v81
	global_store_short v[2:3], v0, off
	v_mul_f32_e32 v0, v22, v47
	v_cvt_pk_bf16_f32 v0, v0, v81
	global_store_short v[2:3], v0, off offset:64
	v_mul_f32_e32 v0, v7, v48
	v_cvt_pk_bf16_f32 v0, v0, v81
	global_store_short v[2:3], v0, off offset:2048
	v_mul_f32_e32 v0, v23, v48
	v_cvt_pk_bf16_f32 v0, v0, v81
	global_store_short v[2:3], v0, off offset:2112
	v_mul_f32_e32 v0, v8, v40
	v_cvt_pk_bf16_f32 v4, v0, v81
	v_add_co_u32_e32 v0, vcc, s49, v32
	v_rcp_f32_e32 v39, v39
	s_nop 0
	v_addc_co_u32_e32 v1, vcc, 0, v33, vcc
	v_add_co_u32_e32 v2, vcc, s54, v32
	s_nop 1
	v_addc_co_u32_e32 v3, vcc, 0, v33, vcc
	global_store_short v[2:3], v4, off offset:-4096
	v_mul_f32_e32 v4, v24, v40
	v_cvt_pk_bf16_f32 v4, v4, v81
	global_store_short v[0:1], v4, off offset:64
	v_mul_f32_e32 v4, v9, v49
	v_cvt_pk_bf16_f32 v4, v4, v81
	global_store_short v[0:1], v4, off offset:2048
	v_mul_f32_e32 v4, v25, v49
	v_cvt_pk_bf16_f32 v4, v4, v81
	global_store_short v[0:1], v4, off offset:2112
	v_mul_f32_e32 v0, v10, v50
	v_cvt_pk_bf16_f32 v0, v0, v81
	global_store_short v[2:3], v0, off
	v_mul_f32_e32 v0, v26, v50
	v_cvt_pk_bf16_f32 v0, v0, v81
	global_store_short v[2:3], v0, off offset:64
	v_mul_f32_e32 v0, v11, v51
	v_cvt_pk_bf16_f32 v0, v0, v81
	global_store_short v[2:3], v0, off offset:2048
	v_mul_f32_e32 v0, v27, v51
	v_cvt_pk_bf16_f32 v0, v0, v81
	global_store_short v[2:3], v0, off offset:2112
	v_mul_f32_e32 v0, v12, v36
	v_cvt_pk_bf16_f32 v4, v0, v81
	v_add_co_u32_e32 v0, vcc, s45, v32
	s_nop 1
	v_addc_co_u32_e32 v1, vcc, 0, v33, vcc
	v_add_co_u32_e32 v2, vcc, s55, v32
	s_nop 1
	v_addc_co_u32_e32 v3, vcc, 0, v33, vcc
	global_store_short v[2:3], v4, off offset:-4096
	v_mul_f32_e32 v4, v28, v36
	v_cvt_pk_bf16_f32 v4, v4, v81
	global_store_short v[0:1], v4, off offset:64
	v_mul_f32_e32 v4, v13, v37
	v_cvt_pk_bf16_f32 v4, v4, v81
	global_store_short v[0:1], v4, off offset:2048
	v_mul_f32_e32 v4, v29, v37
	v_cvt_pk_bf16_f32 v4, v4, v81
	global_store_short v[0:1], v4, off offset:2112
	v_mul_f32_e32 v0, v14, v38
	v_cvt_pk_bf16_f32 v0, v0, v81
	global_store_short v[2:3], v0, off
	v_mul_f32_e32 v0, v30, v38
	v_cvt_pk_bf16_f32 v0, v0, v81
	global_store_short v[2:3], v0, off offset:64
	v_mul_f32_e32 v0, v15, v39
	v_cvt_pk_bf16_f32 v0, v0, v81
	global_store_short v[2:3], v0, off offset:2048
	v_mul_f32_e32 v0, v31, v39
	v_cvt_pk_bf16_f32 v0, v0, v81
	global_store_short v[2:3], v0, off offset:2112
	s_barrier
	s_branch .LBB0_1590

; #define SBAR() __builtin_amdgcn_sched_barrier(0)
; #define ROT() do { const int t_ = bv; bv = bk; bk = bw; bw = t_; } while (0)
; template <int ND> __device__ __forceinline__ void qkt(f32x16& p0, f32x16& p1, const bf16* Ks, const bf16x8* qr, int r32, int hi) {
;   p0 = f32x16{}; p1 = f32x16{};
; #pragma unroll
;   for (int d0 = 0; d0 < ND; ++d0) { int cb = (d0 * 16 + hi * 8) * 2;
;     bf16x8 b0 = *reinterpret_cast<const bf16x8*>((const char*)Ks + KSWZ(r32, cb));
;     bf16x8 b1 = *reinterpret_cast<const bf16x8*>((const char*)Ks + KSWZ(32 + r32, cb));
;     p0 = __builtin_amdgcn_mfma_f32_32x32x16_bf16(b0, qr[d0], p0, 0, 0, 0);
;     p1 = __builtin_amdgcn_mfma_f32_32x32x16_bf16(b1, qr[d0], p1, 0, 0, 0); }
; template <bool SHIFT> __device__ __forceinline__ void attn_dense_body(const bf16* __restrict__ Qb, const bf16* __restrict__ Kh, const bf16* __restrict__ Vh, bf16* __restrict__ Ob, int seq, char* lds, LAS unsigned char* ldsl, float negB, const float* __restrict__ gq, int qpos0) {
;     ...
;   for (int j = 1; j + 1 < NT; j += 2) {
;     DMA(bw, (j + 1) * KVBLK);
;     SBAR(); qkt<SHIFT ? 7 : 6>(pB0, pB1, (bf16*)((char*)K_lds + bk * SHM_K), qr, r32, hi);
;     finishSM(pA0, pA1, l_reg, pa0, pa1, pa2, pa3); SBAR();
;     pv_d0(o, vb0 + bv * (int)SHM_V, pa0, pa1, pa2, pa3); partialSM(pB0);
;     asm volatile("s_waitcnt vmcnt(0)" ::: "memory"); __syncthreads(); ROT();
.LBB0_1603:
	s_mov_b32 s51, s52
	s_lshl_b32 s52, s52, 14
	s_add_i32 s53, s52, 0
	v_lshl_add_u64 v[140:141], s[10:11], 0, v[134:135]
	s_add_i32 s57, s53, s4
	v_lshl_add_u64 v[48:49], v[140:141], 0, s[22:23]
	s_add_i32 m0, s57, 0xc000
	v_lshl_add_u64 v[142:143], s[10:11], 0, v[136:137]
	global_load_lds_dwordx4 v[48:49], off
	v_lshl_add_u64 v[48:49], v[142:143], 0, s[24:25]
	s_add_i32 m0, s57, 0xc400
	v_lshl_add_u64 v[144:145], s[10:11], 0, v[138:139]
	global_load_lds_dwordx4 v[48:49], off
	v_lshl_add_u64 v[48:49], v[144:145], 0, s[26:27]
	s_add_i32 m0, s5, s52
	s_nop 0
	global_load_lds_dwordx4 v[48:49], off
	s_lshl_b32 s52, s33, 14
	s_add_i32 s57, s52, 0
	v_add_u32_e32 v52, s57, v146
	ds_read_b128 v[48:51], v52 offset:49152
	ds_read_b128 v[52:55], v52 offset:57344
	v_add_u32_e32 v171, s57, v149
	v_exp_f32_e32 v189, v33
	v_exp_f32_e32 v218, v34
	s_waitcnt lgkmcnt(0)
	v_mfma_f32_32x32x16_bf16 v[64:79], v[48:51], v[84:87], 0
	v_add_u32_e32 v48, s57, v147
	v_add_u32_e32 v49, s57, v148
	ds_read_b128 v[172:175], v48 offset:49152
	ds_read_b128 v[176:179], v48 offset:57344
	ds_read_b128 v[180:183], v49 offset:49152
	ds_read_b128 v[184:187], v49 offset:57344
	ds_read_b128 v[190:193], v171 offset:49152
	ds_read_b128 v[194:197], v171 offset:57344
	v_add_u32_e32 v171, s57, v150
	ds_read_b128 v[198:201], v171 offset:49152
	ds_read_b128 v[202:205], v171 offset:57344
	v_add_u32_e32 v171, s57, v151
	v_mfma_f32_32x32x16_bf16 v[48:63], v[52:55], v[84:87], 0
	ds_read_b128 v[206:209], v171 offset:49152
	ds_read_b128 v[210:213], v171 offset:57344
	v_add_u32_e32 v171, s57, v154
	v_exp_f32_e32 v219, v35
	v_exp_f32_e32 v220, v40
	v_exp_f32_e32 v221, v41
	v_exp_f32_e32 v222, v42
	v_exp_f32_e32 v47, v47
	s_waitcnt lgkmcnt(0)
	v_mfma_f32_32x32x16_bf16 v[64:79], v[172:175], v[88:91], v[64:79]
	ds_read_b128 v[172:175], v171 offset:49152
	ds_read_b128 v[214:217], v171 offset:57344
	v_exp_f32_e32 v171, v32
	v_add_f32_e32 v32, 0, v168
	v_add_f32_e32 v32, v170, v32
	v_add_f32_e32 v32, v166, v32
	v_add_f32_e32 v32, v169, v32
	v_add_f32_e32 v32, v164, v32
	v_mfma_f32_32x32x16_bf16 v[48:63], v[176:179], v[88:91], v[48:63]
	v_add_f32_e32 v32, v167, v32
	v_add_f32_e32 v32, v163, v32
	v_add_f32_e32 v32, v165, v32
	v_add_f32_e32 v32, v160, v32
	v_add_f32_e32 v32, v162, v32
	v_add_f32_e32 v32, v158, v32
	v_add_f32_e32 v32, v161, v32
	v_mfma_f32_32x32x16_bf16 v[64:79], v[180:183], v[92:95], v[64:79]
	v_add_f32_e32 v32, v156, v32
	v_add_f32_e32 v32, v159, v32
	v_add_f32_e32 v32, v131, v32
	v_add_f32_e32 v32, v157, v32
	v_exp_f32_e32 v176, v36
	v_add_f32_e32 v32, v171, v32
	v_exp_f32_e32 v177, v37
	v_mfma_f32_32x32x16_bf16 v[48:63], v[184:187], v[92:95], v[48:63]
	v_add_f32_e32 v32, v189, v32
	v_exp_f32_e32 v178, v38
	v_add_f32_e32 v32, v218, v32
	v_exp_f32_e32 v179, v39
	v_add_f32_e32 v32, v219, v32
	v_add_f32_e32 v32, v176, v32
	v_add_f32_e32 v32, v177, v32
	v_mfma_f32_32x32x16_bf16 v[64:79], v[190:193], v[96:99], v[64:79]
	v_add_f32_e32 v32, v178, v32
	v_exp_f32_e32 v180, v43
	v_add_f32_e32 v32, v179, v32
	v_exp_f32_e32 v181, v44
	v_add_f32_e32 v32, v220, v32
	v_exp_f32_e32 v182, v45
	v_add_f32_e32 v32, v221, v32
	v_mfma_f32_32x32x16_bf16 v[48:63], v[194:197], v[96:99], v[48:63]
	v_exp_f32_e32 v183, v46
	v_add_f32_e32 v32, v222, v32
	v_add_f32_e32 v32, v180, v32
	v_add_f32_e32 v32, v181, v32
	v_add_f32_e32 v32, v182, v32
	v_add_f32_e32 v32, v183, v32
	v_add_f32_e32 v32, v47, v32
	v_mfma_f32_32x32x16_bf16 v[64:79], v[198:201], v[100:103], v[64:79]
	v_add_f32_e32 v133, v133, v32
	v_cvt_pk_bf16_f32 v32, v168, v170
	v_cvt_pk_bf16_f32 v33, v166, v169
	v_cvt_pk_bf16_f32 v34, v164, v167
	v_cvt_pk_bf16_f32 v35, v163, v165
	v_cvt_pk_bf16_f32 v36, v160, v162
	v_cvt_pk_bf16_f32 v37, v158, v161
	v_mfma_f32_32x32x16_bf16 v[48:63], v[202:205], v[100:103], v[48:63]
	v_cvt_pk_bf16_f32 v38, v156, v159
	v_cvt_pk_bf16_f32 v39, v131, v157
	v_cvt_pk_bf16_f32 v40, v171, v189
	v_cvt_pk_bf16_f32 v41, v218, v219
	v_cvt_pk_bf16_f32 v42, v176, v177
	v_cvt_pk_bf16_f32 v43, v178, v179
	v_cvt_pk_bf16_f32 v44, v220, v221
	v_mfma_f32_32x32x16_bf16 v[64:79], v[206:209], v[104:107], v[64:79]
	v_cvt_pk_bf16_f32 v45, v222, v180
	v_cvt_pk_bf16_f32 v46, v181, v182
	v_cvt_pk_bf16_f32 v47, v183, v47
	v_mfma_f32_32x32x16_bf16 v[48:63], v[210:213], v[104:107], v[48:63]
	s_waitcnt lgkmcnt(0)
	v_mfma_f32_32x32x16_bf16 v[64:79], v[172:175], v[80:83], v[64:79]
	v_mfma_f32_32x32x16_bf16 v[48:63], v[214:217], v[80:83], v[48:63]
	s_lshl_b32 s57, s56, 14
	v_add_u32_e32 v131, s57, v115
	ds_read_b64_tr_b16 v[156:157], v131 offset:0
	ds_read_b64_tr_b16 v[158:159], v131 offset:0x800
	ds_read_b64_tr_b16 v[160:161], v131 offset:0x1000
	ds_read_b64_tr_b16 v[162:163], v131 offset:0x1800
	ds_read_b64_tr_b16 v[164:165], v131 offset:0x2000
	ds_read_b64_tr_b16 v[166:167], v131 offset:0x2800
	ds_read_b64_tr_b16 v[168:169], v131 offset:0x3000
	ds_read_b64_tr_b16 v[170:171], v131 offset:0x3800
	s_waitcnt lgkmcnt(0)
	s_nop 0
	v_mfma_f32_32x32x16_bf16 v[0:15], v[32:35], v[156:159], v[0:15]
	ds_read_b64_tr_b16 v[156:157], v131 offset:0x200
	ds_read_b64_tr_b16 v[158:159], v131 offset:0xa00
	v_mfma_f32_32x32x16_bf16 v[0:15], v[36:39], v[160:163], v[0:15]
	ds_read_b64_tr_b16 v[160:161], v131 offset:0x1200
	ds_read_b64_tr_b16 v[162:163], v131 offset:0x1a00
	v_mfma_f32_32x32x16_bf16 v[0:15], v[40:43], v[164:167], v[0:15]
	ds_read_b64_tr_b16 v[164:165], v131 offset:0x2200
	ds_read_b64_tr_b16 v[166:167], v131 offset:0x2a00
	ds_read_b64_tr_b16 v[172:173], v131 offset:0x3200
	ds_read_b64_tr_b16 v[174:175], v131 offset:0x3a00
	s_waitcnt lgkmcnt(0)
	v_mfma_f32_32x32x16_bf16 v[0:15], v[44:47], v[168:171], v[0:15]
	s_add_i32 s57, s5, s57
	v_lshl_add_u64 v[140:141], v[140:141], 0, s[28:29]
	s_add_i32 m0, s57, 0xc000
	s_waitcnt vmcnt(0)
	s_waitcnt vmcnt(0)
	s_barrier
; #define SBAR() __builtin_amdgcn_sched_barrier(0)
; #define ROT() do { const int t_ = bv; bv = bk; bk = bw; bw = t_; } while (0)
; __device__ __forceinline__ void finishSM(f32x16& p0, f32x16& p1, float& l_reg, bf16x8& pa0, bf16x8& pa1, bf16x8& pa2, bf16x8& pa3) {
; #pragma unroll
;   for (int r = 0; r < 16; ++r) p1[r] = __builtin_amdgcn_exp2f(p1[r]);
;   float ps = 0;
; #pragma unroll
;   for (int r = 0; r < 16; ++r) ps += p0[r];
; #pragma unroll
;   for (int r = 0; r < 16; ++r) ps += p1[r];
;   l_reg += ps;
;     ...
;   PK4(p0, 0, pa0); PK4(p0, 8, pa1); PK4(p1, 0, pa2); PK4(p1, 8, pa3);
;     ...
; }
; template <bool SHIFT> __device__ __forceinline__ void attn_dense_body(const bf16* __restrict__ Qb, const bf16* __restrict__ Kh, const bf16* __restrict__ Vh, bf16* __restrict__ Ob, int seq, char* lds, LAS unsigned char* ldsl, float negB, const float* __restrict__ gq, int qpos0) {
;     ...
;   for (int j = 1; j + 1 < NT; j += 2) {
;     DMA(bw, (j + 1) * KVBLK);
;     SBAR(); qkt<SHIFT ? 7 : 6>(pB0, pB1, (bf16*)((char*)K_lds + bk * SHM_K), qr, r32, hi);
;     finishSM(pA0, pA1, l_reg, pa0, pa1, pa2, pa3); SBAR();
;     pv_d0(o, vb0 + bv * (int)SHM_V, pa0, pa1, pa2, pa3); partialSM(pB0);
;     asm volatile("s_waitcnt vmcnt(0)" ::: "memory"); __syncthreads(); ROT();
;     DMA(bw, (j + 2) * KVBLK);
;     SBAR(); qkt<SHIFT ? 7 : 6>(pA0, pA1, (bf16*)((char*)K_lds + bk * SHM_K), qr, r32, hi);
;     finishSM(pB0, pB1, l_reg, pa0, pa1, pa2, pa3); SBAR();
;     pv_d0(o, vb0 + bv * (int)SHM_V, pa0, pa1, pa2, pa3); partialSM(pA0);
;     asm volatile("s_waitcnt vmcnt(0)" ::: "memory"); __syncthreads(); ROT();
;   }
	v_mfma_f32_32x32x16_bf16 v[16:31], v[32:35], v[156:159], v[16:31]
	global_load_lds_dwordx4 v[140:141], off
	v_lshl_add_u64 v[32:33], v[142:143], 0, s[30:31]
	s_add_i32 m0, s57, 0xc400
	v_exp_f32_e32 v131, v64
	global_load_lds_dwordx4 v[32:33], off
	v_lshl_add_u64 v[32:33], v[144:145], 0, s[34:35]
	s_mov_b32 m0, s57
	v_mfma_f32_32x32x16_bf16 v[16:31], v[36:39], v[160:163], v[16:31]
	global_load_lds_dwordx4 v[32:33], off
	v_exp_f32_e32 v144, v65
	v_exp_f32_e32 v145, v66
	v_exp_f32_e32 v189, v67
	v_exp_f32_e32 v198, v68
	v_exp_f32_e32 v199, v69
	v_mfma_f32_32x32x16_bf16 v[16:31], v[40:43], v[164:167], v[16:31]
	v_exp_f32_e32 v200, v70
	v_exp_f32_e32 v201, v71
	v_exp_f32_e32 v202, v72
	v_exp_f32_e32 v203, v73
	v_exp_f32_e32 v204, v74
	v_exp_f32_e32 v205, v75
	v_exp_f32_e32 v206, v76
	v_mfma_f32_32x32x16_bf16 v[16:31], v[44:47], v[172:175], v[16:31]
	v_exp_f32_e32 v207, v77
	v_exp_f32_e32 v208, v78
	v_exp_f32_e32 v209, v79
	v_add_u32_e32 v36, s53, v146
	ds_read_b128 v[32:35], v36 offset:49152
	ds_read_b128 v[36:39], v36 offset:57344
	v_add_u32_e32 v172, s53, v149
	v_exp_f32_e32 v210, v48
	v_add_f32_e32 v48, 0, v131
	s_waitcnt lgkmcnt(0)
	v_mfma_f32_32x32x16_bf16 v[64:79], v[32:35], v[84:87], 0
	v_add_u32_e32 v32, s53, v147
	v_add_u32_e32 v33, s53, v148
	ds_read_b128 v[140:143], v32 offset:49152
	ds_read_b128 v[156:159], v32 offset:57344
	ds_read_b128 v[160:163], v33 offset:49152
	ds_read_b128 v[164:167], v33 offset:57344
	ds_read_b128 v[168:171], v172 offset:49152
	ds_read_b128 v[172:175], v172 offset:57344
	v_add_f32_e32 v48, v144, v48
	v_add_f32_e32 v48, v145, v48
	v_add_u32_e32 v180, s53, v150
	v_mfma_f32_32x32x16_bf16 v[32:47], v[36:39], v[84:87], 0
	v_add_f32_e32 v48, v189, v48
	ds_read_b128 v[176:179], v180 offset:49152
	ds_read_b128 v[180:183], v180 offset:57344
	v_add_f32_e32 v48, v198, v48
	v_add_f32_e32 v48, v199, v48
	v_add_f32_e32 v48, v200, v48
	v_add_f32_e32 v48, v201, v48
	v_add_f32_e32 v48, v202, v48
	s_waitcnt lgkmcnt(0)
	v_mfma_f32_32x32x16_bf16 v[32:47], v[156:159], v[88:91], v[32:47]
	v_add_f32_e32 v48, v203, v48
	v_add_f32_e32 v48, v204, v48
	v_add_u32_e32 v190, s53, v151
	v_add_f32_e32 v48, v205, v48
	ds_read_b128 v[184:187], v190 offset:49152
	ds_read_b128 v[190:193], v190 offset:57344
	v_add_f32_e32 v48, v206, v48
	v_exp_f32_e32 v211, v49
	v_mfma_f32_32x32x16_bf16 v[64:79], v[140:143], v[88:91], v[64:79]
	v_add_f32_e32 v48, v207, v48
	v_exp_f32_e32 v212, v50
	v_add_f32_e32 v48, v208, v48
	v_exp_f32_e32 v213, v51
	v_add_f32_e32 v48, v209, v48
	v_exp_f32_e32 v156, v52
	v_add_f32_e32 v48, v210, v48
	v_mfma_f32_32x32x16_bf16 v[32:47], v[164:167], v[92:95], v[32:47]
	v_exp_f32_e32 v157, v53
	v_add_f32_e32 v48, v211, v48
	v_exp_f32_e32 v158, v54
	v_add_f32_e32 v48, v212, v48
	v_add_u32_e32 v194, s53, v154
	v_exp_f32_e32 v159, v55
	v_add_f32_e32 v48, v213, v48
	v_mfma_f32_32x32x16_bf16 v[64:79], v[160:163], v[92:95], v[64:79]
	ds_read_b128 v[140:143], v194 offset:49152
	ds_read_b128 v[194:197], v194 offset:57344
	v_exp_f32_e32 v214, v56
	v_add_f32_e32 v48, v156, v48
	v_exp_f32_e32 v215, v57
	v_add_f32_e32 v48, v157, v48
	v_exp_f32_e32 v216, v58
	v_add_f32_e32 v48, v158, v48
	v_mfma_f32_32x32x16_bf16 v[32:47], v[172:175], v[96:99], v[32:47]
	v_exp_f32_e32 v160, v59
	v_add_f32_e32 v48, v159, v48
	v_exp_f32_e32 v161, v60
	v_add_f32_e32 v48, v214, v48
	v_exp_f32_e32 v162, v61
	v_add_f32_e32 v48, v215, v48
	v_exp_f32_e32 v163, v62
	v_mfma_f32_32x32x16_bf16 v[64:79], v[168:171], v[96:99], v[64:79]
	v_add_f32_e32 v48, v216, v48
	v_exp_f32_e32 v63, v63
	v_add_f32_e32 v48, v160, v48
	v_add_f32_e32 v48, v161, v48
	v_add_f32_e32 v48, v162, v48
	v_add_f32_e32 v48, v163, v48
	v_add_f32_e32 v48, v63, v48
	v_mfma_f32_32x32x16_bf16 v[32:47], v[180:183], v[100:103], v[32:47]
	v_add_f32_e32 v133, v133, v48
	v_cvt_pk_bf16_f32 v48, v131, v144
	v_cvt_pk_bf16_f32 v49, v145, v189
	v_cvt_pk_bf16_f32 v50, v198, v199
	v_cvt_pk_bf16_f32 v51, v200, v201
	v_cvt_pk_bf16_f32 v52, v202, v203
	v_cvt_pk_bf16_f32 v53, v204, v205
	v_mfma_f32_32x32x16_bf16 v[64:79], v[176:179], v[100:103], v[64:79]
	v_cvt_pk_bf16_f32 v54, v206, v207
	v_cvt_pk_bf16_f32 v55, v208, v209
	v_cvt_pk_bf16_f32 v56, v210, v211
	v_cvt_pk_bf16_f32 v57, v212, v213
	v_cvt_pk_bf16_f32 v58, v156, v157
	v_cvt_pk_bf16_f32 v59, v158, v159
	v_cvt_pk_bf16_f32 v60, v214, v215
	s_waitcnt lgkmcnt(0)
	v_mfma_f32_32x32x16_bf16 v[32:47], v[190:193], v[104:107], v[32:47]
	v_cvt_pk_bf16_f32 v61, v216, v160
	v_cvt_pk_bf16_f32 v62, v161, v162
	v_cvt_pk_bf16_f32 v63, v163, v63
	v_mfma_f32_32x32x16_bf16 v[64:79], v[184:187], v[104:107], v[64:79]
	v_mfma_f32_32x32x16_bf16 v[32:47], v[194:197], v[80:83], v[32:47]
	v_mfma_f32_32x32x16_bf16 v[64:79], v[140:143], v[80:83], v[64:79]
	v_add_u32_e32 v131, s52, v115
	ds_read_b64_tr_b16 v[140:141], v131 offset:0
	ds_read_b64_tr_b16 v[142:143], v131 offset:0x800
	ds_read_b64_tr_b16 v[156:157], v131 offset:0x1000
	ds_read_b64_tr_b16 v[158:159], v131 offset:0x1800
	ds_read_b64_tr_b16 v[160:161], v131 offset:0x2000
	ds_read_b64_tr_b16 v[162:163], v131 offset:0x2800
	ds_read_b64_tr_b16 v[164:165], v131 offset:0x3000
	ds_read_b64_tr_b16 v[166:167], v131 offset:0x3800
	s_waitcnt lgkmcnt(0)
	s_nop 0
	v_mfma_f32_32x32x16_bf16 v[0:15], v[48:51], v[140:143], v[0:15]
	ds_read_b64_tr_b16 v[140:141], v131 offset:0x200
	ds_read_b64_tr_b16 v[142:143], v131 offset:0xa00
	v_mfma_f32_32x32x16_bf16 v[0:15], v[52:55], v[156:159], v[0:15]
	ds_read_b64_tr_b16 v[156:157], v131 offset:0x1200
	ds_read_b64_tr_b16 v[158:159], v131 offset:0x1a00
	ds_read_b64_tr_b16 v[172:173], v131 offset:0x2200
	ds_read_b64_tr_b16 v[174:175], v131 offset:0x2a00
	ds_read_b64_tr_b16 v[176:177], v131 offset:0x3200
	ds_read_b64_tr_b16 v[178:179], v131 offset:0x3a00
	s_waitcnt lgkmcnt(0)
	v_mfma_f32_32x32x16_bf16 v[0:15], v[56:59], v[160:163], v[0:15]
	v_mfma_f32_32x32x16_bf16 v[0:15], v[60:63], v[164:167], v[0:15]
	v_mfma_f32_32x32x16_bf16 v[16:31], v[48:51], v[140:143], v[16:31]
	s_nop 4
	v_exp_f32_e32 v168, v64
	v_exp_f32_e32 v170, v65
	v_exp_f32_e32 v166, v66
	v_exp_f32_e32 v169, v67
	v_exp_f32_e32 v164, v68
	v_exp_f32_e32 v167, v69
	v_exp_f32_e32 v163, v70
	v_mfma_f32_32x32x16_bf16 v[16:31], v[52:55], v[156:159], v[16:31]
	v_exp_f32_e32 v165, v71
	v_exp_f32_e32 v160, v72
	v_exp_f32_e32 v162, v73
	v_exp_f32_e32 v158, v74
	v_exp_f32_e32 v161, v75
	v_exp_f32_e32 v156, v76
	v_exp_f32_e32 v159, v77
	v_mfma_f32_32x32x16_bf16 v[16:31], v[56:59], v[172:175], v[16:31]
	v_exp_f32_e32 v131, v78
	v_exp_f32_e32 v157, v79
	s_waitcnt vmcnt(0)
	s_add_i32 s50, s50, 2
	v_lshl_add_u64 v[134:135], v[134:135], 0, s[36:37]
	v_lshl_add_u64 v[136:137], v[136:137], 0, s[36:37]
	v_lshl_add_u64 v[138:139], v[138:139], 0, s[16:17]
	v_mfma_f32_32x32x16_bf16 v[16:31], v[60:63], v[176:179], v[16:31]
	s_mov_b32 s52, s33
	s_mov_b32 s33, s56
	s_cmp_gt_u32 s50, 64
	s_mov_b32 s56, s51
	s_waitcnt vmcnt(0)
	s_barrier
; #define SBAR() __builtin_amdgcn_sched_barrier(0)
; #define ROT() do { const int t_ = bv; bv = bk; bk = bw; bw = t_; } while (0)
; __device__ __forceinline__ void finishSM(f32x16& p0, f32x16& p1, float& l_reg, bf16x8& pa0, bf16x8& pa1, bf16x8& pa2, bf16x8& pa3) {
; #pragma unroll
;   for (int r = 0; r < 16; ++r) p1[r] = __builtin_amdgcn_exp2f(p1[r]);
;   float ps = 0;
; #pragma unroll
;   for (int r = 0; r < 16; ++r) ps += p0[r];
; #pragma unroll
;   for (int r = 0; r < 16; ++r) ps += p1[r];
;   l_reg += ps;
;     ...
;   PK4(p0, 0, pa0); PK4(p0, 8, pa1); PK4(p1, 0, pa2); PK4(p1, 8, pa3);
;     ...
; }
; template <bool SHIFT> __device__ __forceinline__ void attn_dense_body(const bf16* __restrict__ Qb, const bf16* __restrict__ Kh, const bf16* __restrict__ Vh, bf16* __restrict__ Ob, int seq, char* lds, LAS unsigned char* ldsl, float negB, const float* __restrict__ gq, int qpos0) {
;     ...
;   SBAR(); qkt<SHIFT ? 7 : 6>(pB0, pB1, (bf16*)((char*)K_lds + bk * SHM_K), qr, r32, hi);
;   finishSM(pA0, pA1, l_reg, pa0, pa1, pa2, pa3); SBAR();
;   pv_d0(o, vb0 + bv * (int)SHM_V, pa0, pa1, pa2, pa3); partialSM(pB0);
;   ROT();
	s_cbranch_scc0 .LBB0_1603
	s_add_i32 s4, 0, 0x10000
	v_add_u32_e32 v52, s4, v146
	ds_read_b128 v[48:51], v52
	ds_read_b128 v[64:67], v52 offset:8192
	v_add_u32_e32 v68, s4, v147
	v_add_u32_e32 v69, s4, v148
	ds_read_b128 v[134:137], v68
	ds_read_b128 v[138:141], v68 offset:8192
	ds_read_b128 v[142:145], v69
	ds_read_b128 v[172:175], v69 offset:8192
	s_waitcnt lgkmcnt(5)
	v_mfma_f32_32x32x16_bf16 v[48:63], v[48:51], v[84:87], 0
	v_add_u32_e32 v171, s4, v149
	v_exp_f32_e32 v189, v33
	v_exp_f32_e32 v202, v34
	v_exp_f32_e32 v203, v35
	v_exp_f32_e32 v47, v47
	s_waitcnt lgkmcnt(4)
	v_mfma_f32_32x32x16_bf16 v[64:79], v[64:67], v[84:87], 0
	ds_read_b128 v[84:87], v171
	ds_read_b128 v[176:179], v171 offset:8192
	v_add_u32_e32 v171, s4, v150
	ds_read_b128 v[180:183], v171
	ds_read_b128 v[184:187], v171 offset:8192
	v_add_u32_e32 v171, s4, v151
	ds_read_b128 v[190:193], v171
	ds_read_b128 v[194:197], v171 offset:8192
	v_add_u32_e32 v171, s4, v154
	s_waitcnt lgkmcnt(9)
	v_mfma_f32_32x32x16_bf16 v[48:63], v[134:137], v[88:91], v[48:63]
	ds_read_b128 v[134:137], v171
	ds_read_b128 v[198:201], v171 offset:8192
	v_exp_f32_e32 v171, v32
	v_add_f32_e32 v32, 0, v168
	v_add_f32_e32 v32, v170, v32
	v_add_f32_e32 v32, v166, v32
	v_add_f32_e32 v32, v169, v32
	v_add_f32_e32 v32, v164, v32
	s_waitcnt lgkmcnt(10)
	v_mfma_f32_32x32x16_bf16 v[64:79], v[138:141], v[88:91], v[64:79]
	v_add_f32_e32 v32, v167, v32
	v_add_f32_e32 v32, v163, v32
	v_add_f32_e32 v32, v165, v32
	v_add_f32_e32 v32, v160, v32
	v_add_f32_e32 v32, v162, v32
	v_add_f32_e32 v32, v158, v32
	v_add_f32_e32 v32, v161, v32
	s_waitcnt lgkmcnt(9)
	v_mfma_f32_32x32x16_bf16 v[48:63], v[142:145], v[92:95], v[48:63]
	v_add_f32_e32 v32, v156, v32
	v_add_f32_e32 v32, v159, v32
	v_add_f32_e32 v32, v131, v32
	v_add_f32_e32 v32, v157, v32
	v_exp_f32_e32 v88, v36
	v_add_f32_e32 v32, v171, v32
	v_exp_f32_e32 v89, v37
	s_waitcnt lgkmcnt(8)
	v_mfma_f32_32x32x16_bf16 v[64:79], v[172:175], v[92:95], v[64:79]
	v_add_f32_e32 v32, v189, v32
	v_exp_f32_e32 v90, v38
	v_add_f32_e32 v32, v202, v32
	v_exp_f32_e32 v91, v39
	v_add_f32_e32 v32, v203, v32
	v_exp_f32_e32 v138, v40
	v_add_f32_e32 v32, v88, v32
	s_waitcnt lgkmcnt(7)
	v_mfma_f32_32x32x16_bf16 v[48:63], v[84:87], v[96:99], v[48:63]
	v_exp_f32_e32 v139, v41
	v_add_f32_e32 v32, v89, v32
	v_exp_f32_e32 v140, v42
	v_add_f32_e32 v32, v90, v32
	v_exp_f32_e32 v141, v43
	v_add_f32_e32 v32, v91, v32
	v_exp_f32_e32 v142, v44
	s_waitcnt lgkmcnt(6)
	v_mfma_f32_32x32x16_bf16 v[64:79], v[176:179], v[96:99], v[64:79]
	v_add_f32_e32 v32, v138, v32
	v_exp_f32_e32 v143, v45
	v_add_f32_e32 v32, v139, v32
	v_exp_f32_e32 v144, v46
	v_add_f32_e32 v32, v140, v32
	v_add_f32_e32 v32, v141, v32
	v_add_f32_e32 v32, v142, v32
	s_waitcnt lgkmcnt(5)
	v_mfma_f32_32x32x16_bf16 v[48:63], v[180:183], v[100:103], v[48:63]
	v_add_f32_e32 v32, v143, v32
	v_add_f32_e32 v32, v144, v32
	v_add_f32_e32 v32, v47, v32
	s_waitcnt lgkmcnt(4)
	v_mfma_f32_32x32x16_bf16 v[64:79], v[184:187], v[100:103], v[64:79]
	v_add_f32_e32 v102, v133, v32
	v_cvt_pk_bf16_f32 v32, v168, v170
	v_cvt_pk_bf16_f32 v33, v166, v169
	v_cvt_pk_bf16_f32 v34, v164, v167
	v_cvt_pk_bf16_f32 v35, v163, v165
	v_cvt_pk_bf16_f32 v36, v160, v162
	v_cvt_pk_bf16_f32 v37, v158, v161
	s_waitcnt lgkmcnt(3)
	v_mfma_f32_32x32x16_bf16 v[48:63], v[190:193], v[104:107], v[48:63]
	v_cvt_pk_bf16_f32 v38, v156, v159
	v_cvt_pk_bf16_f32 v39, v131, v157
	v_cvt_pk_bf16_f32 v40, v171, v189
	s_waitcnt lgkmcnt(2)
	v_mfma_f32_32x32x16_bf16 v[64:79], v[194:197], v[104:107], v[64:79]
	v_cvt_pk_bf16_f32 v41, v202, v203
	v_cvt_pk_bf16_f32 v42, v88, v89
	v_cvt_pk_bf16_f32 v43, v90, v91
	v_cvt_pk_bf16_f32 v44, v138, v139
	v_cvt_pk_bf16_f32 v45, v140, v141
	v_cvt_pk_bf16_f32 v46, v142, v143
	v_cvt_pk_bf16_f32 v47, v144, v47
	s_waitcnt lgkmcnt(1)
	v_mfma_f32_32x32x16_bf16 v[48:63], v[134:137], v[80:83], v[48:63]
	s_waitcnt lgkmcnt(0)
	v_mfma_f32_32x32x16_bf16 v[64:79], v[198:201], v[80:83], v[64:79]
	ds_read_b64_tr_b16 v[82:83], v115 offset:0
	ds_read_b64_tr_b16 v[84:85], v115 offset:0x800
	ds_read_b64_tr_b16 v[86:87], v115 offset:0x1000
	ds_read_b64_tr_b16 v[88:89], v115 offset:0x1800
	ds_read_b64_tr_b16 v[90:91], v115 offset:0x2000
	ds_read_b64_tr_b16 v[92:93], v115 offset:0x2800
	ds_read_b64_tr_b16 v[94:95], v115 offset:0x3000
	ds_read_b64_tr_b16 v[96:97], v115 offset:0x3800
	s_waitcnt lgkmcnt(0)
; #define SBAR() __builtin_amdgcn_sched_barrier(0)
; #define ROT() do { const int t_ = bv; bv = bk; bk = bw; bw = t_; } while (0)
; __device__ __forceinline__ void finishSM(f32x16& p0, f32x16& p1, float& l_reg, bf16x8& pa0, bf16x8& pa1, bf16x8& pa2, bf16x8& pa3) {
; #pragma unroll
;   for (int r = 0; r < 16; ++r) p1[r] = __builtin_amdgcn_exp2f(p1[r]);
;   float ps = 0;
; #pragma unroll
;   for (int r = 0; r < 16; ++r) ps += p0[r];
; #pragma unroll
;   for (int r = 0; r < 16; ++r) ps += p1[r];
;   l_reg += ps;
;     ...
;   PK4(p0, 0, pa0); PK4(p0, 8, pa1); PK4(p1, 0, pa2); PK4(p1, 8, pa3);
;     ...
; }
; template <bool SHIFT> __device__ __forceinline__ void attn_dense_body(const bf16* __restrict__ Qb, const bf16* __restrict__ Kh, const bf16* __restrict__ Vh, bf16* __restrict__ Ob, int seq, char* lds, LAS unsigned char* ldsl, float negB, const float* __restrict__ gq, int qpos0) {
;     ...
;   pv_d0(o, vb0 + bv * (int)SHM_V, pa0, pa1, pa2, pa3); partialSM(pB0);
;   ROT();
;   finishSM(pB0, pB1, l_reg, pa0, pa1, pa2, pa3); SBAR();
;   pv_d0(o, vb0 + bv * (int)SHM_V, pa0, pa1, pa2, pa3);
;     ...
;   { auto rr = __builtin_amdgcn_permlane32_swap(__float_as_uint(l_reg), __float_as_uint(l_reg), false, false); l_reg = __uint_as_float(rr[0]) + __uint_as_float(rr[1]); }
;   if (hi == 0) li_l[r32] = l_reg; asm volatile("s_waitcnt lgkmcnt(0)" ::: "memory");
	s_nop 0
	v_mfma_f32_32x32x16_bf16 v[0:15], v[32:35], v[82:85], v[0:15]
	ds_read_b64_tr_b16 v[82:83], v115 offset:0x200
	ds_read_b64_tr_b16 v[84:85], v115 offset:0xa00
	v_mfma_f32_32x32x16_bf16 v[0:15], v[36:39], v[86:89], v[0:15]
	ds_read_b64_tr_b16 v[86:87], v115 offset:0x1200
	ds_read_b64_tr_b16 v[88:89], v115 offset:0x1a00
	v_mfma_f32_32x32x16_bf16 v[0:15], v[40:43], v[90:93], v[0:15]
	ds_read_b64_tr_b16 v[90:91], v115 offset:0x2200
	ds_read_b64_tr_b16 v[92:93], v115 offset:0x2a00
	ds_read_b64_tr_b16 v[98:99], v115 offset:0x3200
	ds_read_b64_tr_b16 v[100:101], v115 offset:0x3a00
	s_waitcnt lgkmcnt(0)
	v_mfma_f32_32x32x16_bf16 v[0:15], v[44:47], v[94:97], v[0:15]
	s_nop 0
	v_exp_f32_e32 v48, v48
	v_exp_f32_e32 v49, v49
	v_exp_f32_e32 v50, v50
	v_exp_f32_e32 v51, v51
	v_mfma_f32_32x32x16_bf16 v[16:31], v[32:35], v[82:85], v[16:31]
	v_exp_f32_e32 v52, v52
	v_add_f32_e32 v32, 0, v48
	v_exp_f32_e32 v53, v53
	v_add_f32_e32 v32, v49, v32
	v_exp_f32_e32 v33, v54
	v_add_f32_e32 v32, v50, v32
	v_exp_f32_e32 v54, v55
	v_add_f32_e32 v32, v51, v32
	v_exp_f32_e32 v55, v56
	v_add_f32_e32 v32, v52, v32
	v_exp_f32_e32 v56, v57
	v_add_f32_e32 v32, v53, v32
	v_exp_f32_e32 v57, v58
	v_add_f32_e32 v32, v33, v32
	v_exp_f32_e32 v58, v59
	v_mfma_f32_32x32x16_bf16 v[16:31], v[36:39], v[86:89], v[16:31]
	v_add_f32_e32 v32, v54, v32
	v_exp_f32_e32 v59, v60
	v_add_f32_e32 v32, v55, v32
	v_exp_f32_e32 v60, v61
	v_add_f32_e32 v32, v56, v32
	v_exp_f32_e32 v61, v62
	v_add_f32_e32 v32, v57, v32
	v_exp_f32_e32 v62, v63
	v_add_f32_e32 v32, v58, v32
	v_exp_f32_e32 v63, v64
	v_add_f32_e32 v32, v59, v32
	v_exp_f32_e32 v64, v65
	v_add_f32_e32 v32, v60, v32
	v_exp_f32_e32 v65, v66
	v_add_f32_e32 v32, v61, v32
	v_exp_f32_e32 v66, v67
	v_mfma_f32_32x32x16_bf16 v[16:31], v[40:43], v[90:93], v[16:31]
	v_add_f32_e32 v32, v62, v32
	v_exp_f32_e32 v67, v68
	v_add_f32_e32 v32, v63, v32
	v_exp_f32_e32 v68, v69
	v_add_f32_e32 v32, v64, v32
	v_exp_f32_e32 v69, v70
	v_add_f32_e32 v32, v65, v32
	v_exp_f32_e32 v70, v71
	v_add_f32_e32 v32, v66, v32
	v_exp_f32_e32 v71, v72
	v_add_f32_e32 v32, v67, v32
	v_exp_f32_e32 v72, v73
	v_add_f32_e32 v32, v68, v32
	v_exp_f32_e32 v73, v74
	v_add_f32_e32 v32, v69, v32
	v_mfma_f32_32x32x16_bf16 v[16:31], v[44:47], v[98:101], v[16:31]
	v_exp_f32_e32 v47, v75
	v_add_f32_e32 v32, v70, v32
	v_exp_f32_e32 v74, v76
	v_add_f32_e32 v32, v71, v32
	v_exp_f32_e32 v75, v77
	v_add_f32_e32 v32, v72, v32
	v_exp_f32_e32 v76, v78
	v_add_f32_e32 v32, v73, v32
	v_exp_f32_e32 v77, v79
	v_add_f32_e32 v32, v47, v32
	v_add_f32_e32 v32, v74, v32
	v_add_f32_e32 v32, v75, v32
	v_add_f32_e32 v32, v76, v32
	v_add_f32_e32 v32, v77, v32
	v_add_f32_e32 v32, v102, v32
	v_cvt_pk_bf16_f32 v34, v48, v49
	v_cvt_pk_bf16_f32 v35, v50, v51
	v_cvt_pk_bf16_f32 v36, v52, v53
	v_cvt_pk_bf16_f32 v37, v33, v54
	v_cvt_pk_bf16_f32 v38, v55, v56
	v_cvt_pk_bf16_f32 v39, v57, v58
	v_cvt_pk_bf16_f32 v40, v59, v60
	v_cvt_pk_bf16_f32 v41, v61, v62
	v_cvt_pk_bf16_f32 v42, v63, v64
	v_cvt_pk_bf16_f32 v43, v65, v66
	v_cvt_pk_bf16_f32 v44, v67, v68
	v_cvt_pk_bf16_f32 v45, v69, v70
	v_cvt_pk_bf16_f32 v46, v71, v72
	v_cvt_pk_bf16_f32 v47, v73, v47
	v_cvt_pk_bf16_f32 v48, v74, v75
	v_cvt_pk_bf16_f32 v49, v76, v77
	s_nop 0
	ds_read_b64_tr_b16 v[50:51], v152 offset:0
	ds_read_b64_tr_b16 v[52:53], v152 offset:0x800
	ds_read_b64_tr_b16 v[54:55], v152 offset:0x1000
	ds_read_b64_tr_b16 v[56:57], v152 offset:0x1800
	ds_read_b64_tr_b16 v[58:59], v152 offset:0x2000
	ds_read_b64_tr_b16 v[60:61], v152 offset:0x2800
	ds_read_b64_tr_b16 v[62:63], v152 offset:0x3000
	ds_read_b64_tr_b16 v[64:65], v152 offset:0x3800
	s_waitcnt lgkmcnt(0)
	s_nop 0
	v_mfma_f32_32x32x16_bf16 v[0:15], v[34:37], v[50:53], v[0:15]
	ds_read_b64_tr_b16 v[50:51], v152 offset:0x200
	ds_read_b64_tr_b16 v[52:53], v152 offset:0xa00
	v_mfma_f32_32x32x16_bf16 v[0:15], v[38:41], v[54:57], v[0:15]
	ds_read_b64_tr_b16 v[54:55], v152 offset:0x1200
	ds_read_b64_tr_b16 v[56:57], v152 offset:0x1a00
	v_mfma_f32_32x32x16_bf16 v[0:15], v[42:45], v[58:61], v[0:15]
	ds_read_b64_tr_b16 v[58:59], v152 offset:0x2200
	ds_read_b64_tr_b16 v[60:61], v152 offset:0x2a00
	ds_read_b64_tr_b16 v[66:67], v152 offset:0x3200
	ds_read_b64_tr_b16 v[68:69], v152 offset:0x3a00
	s_waitcnt lgkmcnt(0)
	v_mfma_f32_32x32x16_bf16 v[0:15], v[46:49], v[62:65], v[0:15]
	v_mfma_f32_32x32x16_bf16 v[16:31], v[34:37], v[50:53], v[16:31]
	v_mov_b32_e32 v33, v32
	s_nop 1
	v_permlane32_swap_b32_e32 v32, v33
	v_mfma_f32_32x32x16_bf16 v[16:31], v[38:41], v[54:57], v[16:31]
	v_mfma_f32_32x32x16_bf16 v[16:31], v[42:45], v[58:61], v[16:31]
	v_mfma_f32_32x32x16_bf16 v[16:31], v[46:49], v[66:69], v[16:31]
	s_and_saveexec_b64 s[4:5], s[6:7]
	s_cbranch_execz .LBB0_1589
	v_add_f32_e32 v32, v32, v33
	ds_write_b32 v153, v32
	s_branch .LBB0_1589
